# v18 + half-peel: only the first two sub-phases of each GEMM tile's K-loop are peeled (zero-C MFMAs), then a jump into the middle of the loop
# speedup vs baseline: 1.0098x; 1.0098x over previous
; #define PG8_STAGE(bufoff, gbase, voff) do { _Pragma("unroll") for (int _i = 0; _i < 2; ++_i) \
;         __builtin_amdgcn_global_load_lds((const unsigned*)((const char*)(gbase) + (voff)[_i]), (PG8_LAS unsigned*)(lds + (bufoff) + ldsw + _i * 8192), 16, 0, 0); } while (0)
; #define PG8_LDA(dst, b, h) do { _Pragma("unroll") for (int m = 0; m < 4; ++m) _Pragma("unroll") for (int k = 0; k < 2; ++k) dst[m][k] = *(const PG8_LAS bf16x8*)(lds + PG8_SA(b, h) + aoff + m * 2048 + k * 1024); } while (0)
; #define PG8_LDB(dst, b, h) do { _Pragma("unroll") for (int n = 0; n < 2; ++n) _Pragma("unroll") for (int k = 0; k < 2; ++k) dst[n][k] = *(const PG8_LAS bf16x8*)(lds + PG8_SB(b, h) + boff + n * 2048 + k * 1024); } while (0)
; #define PG8_WAIT_V(n) asm volatile("s_waitcnt vmcnt(" #n ")" ::: "memory")
; #define PG8_WAIT_L(n) asm volatile("s_waitcnt lgkmcnt(" #n ")" ::: "memory")
; template <class Epi, class Sched, bool ALIGN_EPI = false>
; __device__ __forceinline__ void gemm_phase8(PG8_LAS unsigned char* lds, const Gemm g, const Sched& S, const Epi& E) {
;     ...
;         const bool has_next = S.next(ui + 1, nxt);
;         const size_t nko = (has_next && nxt.kp > 0) ? (size_t)nxt.kp * g.kpiece : 0;
;         const char* nA = has_next ? (const char*)g.A + (size_t)nxt.pm * tstepA + (size_t)nxt.pn * astep + nko : cA; const char* nB = has_next ? (const char*)g.Bt + (size_t)nxt.pn * tstepB + nko : cB;
;         const int nt = (cur.kp < 0 ? g.K : g.kpiece) / 128;
;         for (int t = 0; t < nt; t += 2) {
;             const bool last = (t == nt - 2);
;             const char* a1 = cA + (size_t)(t + 1) * kstep;
;             const char* a2 = last ? nA : cA + (size_t)(t + 2) * kstep; const char* b2 = last ? nB : cB + (size_t)(t + 2) * kstep;
;             const char* a3 = a2 + kstep; const char* b3 = b2 + kstep;
;             if (last && has_next) S.a_ready(nxt);
;             PG8_LDB(B0, 0, 0); PG8_LDB(B1, 0, 1); PG8_SCHED; PG8_LDA(At, 0, 0); PG8_STAGE(PG8_SA(1, 1), a1 + hstepA, voffA);
;             PG8_WAIT_V(8); PG8_WAIT_L(0); PG8_BAR; PG8_MMA(0, 0, At, B0); PG8_MMA(0, 1, At, B1); PG8_BAR; PG8_SCHED;
;             PG8_LDA(At, 0, 1); PG8_STAGE(PG8_SB(0, 0), b2, voffB); PG8_STAGE(PG8_SB(0, 1), b2 + hstepB, voffB); PG8_STAGE(PG8_SA(0, 0), a2, voffA);
;             PG8_WAIT_V(8); PG8_WAIT_L(0); PG8_BAR; PG8_MMA(1, 0, At, B0); PG8_MMA(1, 1, At, B1); PG8_BAR; PG8_SCHED;
.LBB0_324:
	s_ashr_i32 s15, s14, 31
	s_lshl_b64 s[16:17], s[14:15], 19
	s_add_u32 s16, s28, s16
	s_addc_u32 s17, s29, s17
	s_and_b64 s[18:19], s[2:3], exec
	s_cselect_b32 s15, s17, s23
	s_cselect_b32 s61, s16, s22
	s_ashr_i32 s13, s12, 31
	s_lshl_b64 s[18:19], s[12:13], 19
	s_add_u32 s18, s4, s18
	s_addc_u32 s19, s5, s19
	s_and_b64 s[26:27], s[2:3], exec
	s_cselect_b32 s13, s19, s25
	s_cselect_b32 s62, s18, s24
	s_add_u32 s22, s22, 0x40080
	s_addc_u32 s23, s23, 0
	s_add_u32 s63, s24, 0x100
	s_addc_u32 s64, s25, 0
	s_mov_b32 s65, -2
	ds_read_b128 v[18:21], v191
	ds_read_b128 v[26:29], v191 offset:2048
	ds_read_b128 v[22:25], v192
	ds_read_b128 v[30:33], v192 offset:2048
	ds_read_b128 v[2:5], v193
	ds_read_b128 v[10:13], v193 offset:2048
	ds_read_b128 v[6:9], v194
	ds_read_b128 v[14:17], v194 offset:2048
	s_add_u32 s24, s22, 0xfffc0080
	s_addc_u32 s25, s23, -1
	s_cmp_eq_u32 s65, 12
	s_cselect_b32 s27, s15, s25
	s_cselect_b32 s26, s61, s24
	s_cselect_b32 s25, s13, s64
	s_cselect_b32 s24, s62, s63
	s_add_i32 m0, s21, 0xc000
	ds_read_b128 v[178:181], v195
	ds_read_b128 v[198:201], v195 offset:2048
	ds_read_b128 v[182:185], v196
	ds_read_b128 v[202:205], v196 offset:2048
	ds_read_b128 v[206:209], v195 offset:4096
	ds_read_b128 v[214:217], v195 offset:6144
	ds_read_b128 v[210:213], v196 offset:4096
	ds_read_b128 v[218:221], v196 offset:6144
	global_load_lds_dwordx4 v170, s[22:23]
	s_add_i32 m0, s21, 0xe000
	s_nop 0
	global_load_lds_dwordx4 v172, s[22:23]
	s_waitcnt vmcnt(8)
	s_waitcnt lgkmcnt(0)
	s_barrier
	s_setprio 1
	s_waitcnt lgkmcnt(0)
	v_mfma_scale_f32_16x16x128_f8f6f4 v[158:161], v[18:25], v[178:185], 0, v1, v186 op_sel_hi:[0,0,0]
	v_mfma_scale_f32_16x16x128_f8f6f4 v[150:153], v[26:33], v[178:185], 0, v1, v186 op_sel_hi:[0,0,0]
	v_mfma_scale_f32_16x16x128_f8f6f4 v[142:145], v[18:25], v[198:205], 0, v1, v186 op_sel_hi:[0,0,0]
	v_mfma_scale_f32_16x16x128_f8f6f4 v[134:137], v[26:33], v[198:205], 0, v1, v186 op_sel_hi:[0,0,0]
	v_mfma_scale_f32_16x16x128_f8f6f4 v[126:129], v[18:25], v[206:213], 0, v1, v186 op_sel_hi:[0,0,0]
	v_mfma_scale_f32_16x16x128_f8f6f4 v[118:121], v[26:33], v[206:213], 0, v1, v186 op_sel_hi:[0,0,0]
	v_mfma_scale_f32_16x16x128_f8f6f4 v[110:113], v[18:25], v[214:221], 0, v1, v186 op_sel_hi:[0,0,0]
	v_mfma_scale_f32_16x16x128_f8f6f4 v[102:105], v[26:33], v[214:221], 0, v1, v186 op_sel_hi:[0,0,0]
	s_setprio 0
	s_setprio 1
	v_mfma_scale_f32_16x16x128_f8f6f4 v[154:157], v[2:9], v[178:185], 0, v1, v186 op_sel_hi:[0,0,0]
	v_mfma_scale_f32_16x16x128_f8f6f4 v[146:149], v[10:17], v[178:185], 0, v1, v186 op_sel_hi:[0,0,0]
	v_mfma_scale_f32_16x16x128_f8f6f4 v[138:141], v[2:9], v[198:205], 0, v1, v186 op_sel_hi:[0,0,0]
	v_mfma_scale_f32_16x16x128_f8f6f4 v[130:133], v[10:17], v[198:205], 0, v1, v186 op_sel_hi:[0,0,0]
	v_mfma_scale_f32_16x16x128_f8f6f4 v[122:125], v[2:9], v[206:213], 0, v1, v186 op_sel_hi:[0,0,0]
	v_mfma_scale_f32_16x16x128_f8f6f4 v[114:117], v[10:17], v[206:213], 0, v1, v186 op_sel_hi:[0,0,0]
	v_mfma_scale_f32_16x16x128_f8f6f4 v[106:109], v[2:9], v[214:221], 0, v1, v186 op_sel_hi:[0,0,0]
	v_mfma_scale_f32_16x16x128_f8f6f4 v[98:101], v[10:17], v[214:221], 0, v1, v186 op_sel_hi:[0,0,0]
	s_setprio 0
	s_barrier
	s_add_i32 s66, s57, s30
	s_mov_b32 m0, s66
	ds_read_b128 v[198:201], v195 offset:16384
	ds_read_b128 v[206:209], v195 offset:18432
	ds_read_b128 v[202:205], v196 offset:16384
	ds_read_b128 v[210:213], v196 offset:18432
	ds_read_b128 v[214:217], v195 offset:20480
	ds_read_b128 v[222:225], v195 offset:22528
	ds_read_b128 v[218:221], v196 offset:20480
	ds_read_b128 v[226:229], v196 offset:22528
	global_load_lds_dwordx4 v164, s[24:25]
	s_add_i32 m0, s66, 0x2000
	s_add_u32 s66, s24, 0x40000
	s_addc_u32 s67, s25, 0
	s_add_i32 s72, s58, s30
	global_load_lds_dwordx4 v168, s[24:25]
	s_mov_b32 m0, s72
	s_nop 0
	global_load_lds_dwordx4 v164, s[66:67]
	s_add_i32 m0, s72, 0x2000
	s_nop 0
	global_load_lds_dwordx4 v168, s[66:67]
	s_mov_b32 m0, s21
	s_nop 0
	global_load_lds_dwordx4 v162, s[26:27]
	s_mov_b32 m0, s34
	s_nop 0
	global_load_lds_dwordx4 v166, s[26:27]
	s_waitcnt vmcnt(8)
	s_waitcnt lgkmcnt(0)
	s_barrier
	s_setprio 1
	s_waitcnt lgkmcnt(0)
	v_mfma_scale_f32_16x16x128_f8f6f4 v[94:97], v[18:25], v[198:205], 0, v1, v186 op_sel_hi:[0,0,0]
	v_mfma_scale_f32_16x16x128_f8f6f4 v[86:89], v[26:33], v[198:205], 0, v1, v186 op_sel_hi:[0,0,0]
	v_mfma_scale_f32_16x16x128_f8f6f4 v[78:81], v[18:25], v[206:213], 0, v1, v186 op_sel_hi:[0,0,0]
	v_mfma_scale_f32_16x16x128_f8f6f4 v[70:73], v[26:33], v[206:213], 0, v1, v186 op_sel_hi:[0,0,0]
	v_mfma_scale_f32_16x16x128_f8f6f4 v[62:65], v[18:25], v[214:221], 0, v1, v186 op_sel_hi:[0,0,0]
	v_mfma_scale_f32_16x16x128_f8f6f4 v[54:57], v[26:33], v[214:221], 0, v1, v186 op_sel_hi:[0,0,0]
	v_mfma_scale_f32_16x16x128_f8f6f4 v[46:49], v[18:25], v[222:229], 0, v1, v186 op_sel_hi:[0,0,0]
	v_mfma_scale_f32_16x16x128_f8f6f4 v[38:41], v[26:33], v[222:229], 0, v1, v186 op_sel_hi:[0,0,0]
	s_setprio 0
	s_setprio 1
	v_mfma_scale_f32_16x16x128_f8f6f4 v[90:93], v[2:9], v[198:205], 0, v1, v186 op_sel_hi:[0,0,0]
	v_mfma_scale_f32_16x16x128_f8f6f4 v[82:85], v[10:17], v[198:205], 0, v1, v186 op_sel_hi:[0,0,0]
	v_mfma_scale_f32_16x16x128_f8f6f4 v[74:77], v[2:9], v[206:213], 0, v1, v186 op_sel_hi:[0,0,0]
	v_mfma_scale_f32_16x16x128_f8f6f4 v[66:69], v[10:17], v[206:213], 0, v1, v186 op_sel_hi:[0,0,0]
	v_mfma_scale_f32_16x16x128_f8f6f4 v[58:61], v[2:9], v[214:221], 0, v1, v186 op_sel_hi:[0,0,0]
	v_mfma_scale_f32_16x16x128_f8f6f4 v[50:53], v[10:17], v[214:221], 0, v1, v186 op_sel_hi:[0,0,0]
	v_mfma_scale_f32_16x16x128_f8f6f4 v[42:45], v[2:9], v[222:229], 0, v1, v186 op_sel_hi:[0,0,0]
	v_mfma_scale_f32_16x16x128_f8f6f4 v[34:37], v[10:17], v[222:229], 0, v1, v186 op_sel_hi:[0,0,0]
	s_setprio 0
	s_barrier
	s_branch .Lmid_0

; #define PG8_STAGE(bufoff, gbase, voff) do { _Pragma("unroll") for (int _i = 0; _i < 2; ++_i) \
;         __builtin_amdgcn_global_load_lds((const unsigned*)((const char*)(gbase) + (voff)[_i]), (PG8_LAS unsigned*)(lds + (bufoff) + ldsw + _i * 8192), 16, 0, 0); } while (0)
; #define PG8_LDA(dst, b, h) do { _Pragma("unroll") for (int m = 0; m < 4; ++m) _Pragma("unroll") for (int k = 0; k < 2; ++k) dst[m][k] = *(const PG8_LAS bf16x8*)(lds + PG8_SA(b, h) + aoff + m * 2048 + k * 1024); } while (0)
; #define PG8_LDB(dst, b, h) do { _Pragma("unroll") for (int n = 0; n < 2; ++n) _Pragma("unroll") for (int k = 0; k < 2; ++k) dst[n][k] = *(const PG8_LAS bf16x8*)(lds + PG8_SB(b, h) + boff + n * 2048 + k * 1024); } while (0)
; #define PG8_MMA(ai, bj, At, Bt) do { __builtin_amdgcn_s_setprio(1); _Pragma("unroll") for (int m = 0; m < 4; ++m) _Pragma("unroll") for (int n = 0; n < 2; ++n) _Pragma("unroll") for (int k = 0; k < 2; ++k) \
;         acc[ai][bj][m][n] = __builtin_amdgcn_mfma_f32_16x16x32_bf16(Bt[n][k], At[m][k], acc[ai][bj][m][n], 0, 0, 0); __builtin_amdgcn_s_setprio(0); } while (0)
; #define PG8_WAIT_V(n) asm volatile("s_waitcnt vmcnt(" #n ")" ::: "memory")
; #define PG8_WAIT_L(n) asm volatile("s_waitcnt lgkmcnt(" #n ")" ::: "memory")
; #define PG8_BAR __builtin_amdgcn_s_barrier()
; #define PG8_SCHED __builtin_amdgcn_sched_barrier(0)
; #define PG8_STAGE(bufoff, gbase, voff) do { _Pragma("unroll") for (int _i = 0; _i < 2; ++_i) \
;         __builtin_amdgcn_global_load_lds((const unsigned*)((const char*)(gbase) + (voff)[_i]), (PG8_LAS unsigned*)(lds + (bufoff) + ldsw + _i * 8192), 16, 0, 0); } while (0)
; template <class Epi, class Sched, bool ALIGN_EPI = false>
; __device__ __forceinline__ void gemm_phase8(PG8_LAS unsigned char* lds, const Gemm g, const Sched& S, const Epi& E) {
;     ...
;             PG8_LDB(B0, 1, 0); PG8_LDB(B1, 1, 1); PG8_SCHED; PG8_LDA(At, 1, 0); PG8_STAGE(PG8_SA(0, 1), a2 + hstepA, voffA);
;             PG8_WAIT_V(8); PG8_WAIT_L(0); PG8_BAR; PG8_MMA(0, 0, At, B0); PG8_MMA(0, 1, At, B1); PG8_BAR; PG8_SCHED;
;             PG8_LDA(At, 1, 1); PG8_STAGE(PG8_SB(1, 0), b3, voffB); PG8_STAGE(PG8_SB(1, 1), b3 + hstepB, voffB); PG8_STAGE(PG8_SA(1, 0), a3, voffA);
;             PG8_WAIT_V(8); PG8_WAIT_L(0); PG8_BAR; PG8_MMA(1, 0, At, B0); PG8_MMA(1, 1, At, B1); PG8_BAR; PG8_SCHED;
;         }
;         if constexpr (ALIGN_EPI) { if (wr == 0) PG8_BAR; }
.Lmid_0:
	s_add_i32 s66, 0, 0x18000
	s_add_i32 s67, 0, 0x1c000
	v_add_u32_e32 v6, s66, v187
	v_add_u32_e32 v14, s66, v188
	v_add_u32_e32 v22, s67, v187
	v_add_u32_e32 v30, s67, v188
	ds_read_b128 v[2:5], v6
	ds_read_b128 v[10:13], v6 offset:2048
	ds_read_b128 v[6:9], v14
	ds_read_b128 v[14:17], v14 offset:2048
	ds_read_b128 v[18:21], v22
	ds_read_b128 v[26:29], v22 offset:2048
	ds_read_b128 v[22:25], v30
	ds_read_b128 v[30:33], v30 offset:2048
	s_add_u32 s26, s26, 0x40000
	s_addc_u32 s27, s27, 0
	s_mov_b32 m0, s35
	ds_read_b128 v[198:201], v195 offset:32768
	ds_read_b128 v[206:209], v195 offset:34816
	ds_read_b128 v[202:205], v196 offset:32768
	ds_read_b128 v[210:213], v196 offset:34816
	ds_read_b128 v[214:217], v195 offset:36864
	ds_read_b128 v[222:225], v195 offset:38912
	ds_read_b128 v[218:221], v196 offset:36864
	ds_read_b128 v[226:229], v196 offset:38912
	global_load_lds_dwordx4 v162, s[26:27]
	s_mov_b32 m0, s52
	s_nop 0
	global_load_lds_dwordx4 v166, s[26:27]
	s_waitcnt vmcnt(8)
	s_waitcnt lgkmcnt(0)
	s_barrier
	s_setprio 1
	s_waitcnt lgkmcnt(0)
	v_mfma_scale_f32_16x16x128_f8f6f4 v[158:161], v[2:9], v[198:205], v[158:161], v1, v186 op_sel_hi:[0,0,0]
	v_mfma_scale_f32_16x16x128_f8f6f4 v[150:153], v[10:17], v[198:205], v[150:153], v1, v186 op_sel_hi:[0,0,0]
	v_mfma_scale_f32_16x16x128_f8f6f4 v[142:145], v[2:9], v[206:213], v[142:145], v1, v186 op_sel_hi:[0,0,0]
	v_mfma_scale_f32_16x16x128_f8f6f4 v[134:137], v[10:17], v[206:213], v[134:137], v1, v186 op_sel_hi:[0,0,0]
	v_mfma_scale_f32_16x16x128_f8f6f4 v[126:129], v[2:9], v[214:221], v[126:129], v1, v186 op_sel_hi:[0,0,0]
	v_mfma_scale_f32_16x16x128_f8f6f4 v[118:121], v[10:17], v[214:221], v[118:121], v1, v186 op_sel_hi:[0,0,0]
	v_mfma_scale_f32_16x16x128_f8f6f4 v[110:113], v[2:9], v[222:229], v[110:113], v1, v186 op_sel_hi:[0,0,0]
	v_mfma_scale_f32_16x16x128_f8f6f4 v[102:105], v[10:17], v[222:229], v[102:105], v1, v186 op_sel_hi:[0,0,0]
	s_setprio 0
	s_setprio 1
	v_mfma_scale_f32_16x16x128_f8f6f4 v[154:157], v[18:25], v[198:205], v[154:157], v1, v186 op_sel_hi:[0,0,0]
	v_mfma_scale_f32_16x16x128_f8f6f4 v[146:149], v[26:33], v[198:205], v[146:149], v1, v186 op_sel_hi:[0,0,0]
	v_mfma_scale_f32_16x16x128_f8f6f4 v[138:141], v[18:25], v[206:213], v[138:141], v1, v186 op_sel_hi:[0,0,0]
	v_mfma_scale_f32_16x16x128_f8f6f4 v[130:133], v[26:33], v[206:213], v[130:133], v1, v186 op_sel_hi:[0,0,0]
	v_mfma_scale_f32_16x16x128_f8f6f4 v[122:125], v[18:25], v[214:221], v[122:125], v1, v186 op_sel_hi:[0,0,0]
	v_mfma_scale_f32_16x16x128_f8f6f4 v[114:117], v[26:33], v[214:221], v[114:117], v1, v186 op_sel_hi:[0,0,0]
	v_mfma_scale_f32_16x16x128_f8f6f4 v[106:109], v[18:25], v[222:229], v[106:109], v1, v186 op_sel_hi:[0,0,0]
	v_mfma_scale_f32_16x16x128_f8f6f4 v[98:101], v[26:33], v[222:229], v[98:101], v1, v186 op_sel_hi:[0,0,0]
	s_setprio 0
	s_barrier
	s_add_i32 s101, s66, s30
	s_add_u32 s98, s24, s8
	s_addc_u32 s99, s25, s9
	s_mov_b32 m0, s101
	ds_read_b128 v[198:201], v195 offset:49152
	ds_read_b128 v[206:209], v195 offset:51200
	ds_read_b128 v[202:205], v196 offset:49152
	ds_read_b128 v[210:213], v196 offset:51200
	ds_read_b128 v[214:217], v195 offset:53248
	ds_read_b128 v[222:225], v195 offset:55296
	ds_read_b128 v[218:221], v196 offset:53248
	ds_read_b128 v[226:229], v196 offset:55296
	global_load_lds_dwordx4 v164, s[98:99]
	s_add_i32 m0, s101, 0x2000
	s_add_u32 s24, s24, 0x40080
	s_addc_u32 s25, s25, 0
	s_add_i32 s101, s67, s30
	global_load_lds_dwordx4 v168, s[98:99]
	s_add_u32 s98, s26, s8
	s_addc_u32 s99, s27, s9
	s_sub_u32 s98, s98, 0x40000
	s_subb_u32 s99, s99, 0
	s_mov_b32 m0, s101
	s_nop 0
	global_load_lds_dwordx4 v164, s[24:25]
	s_add_i32 m0, s101, 0x2000
	s_nop 0
	global_load_lds_dwordx4 v168, s[24:25]
	s_mov_b32 m0, s55
	s_nop 0
	global_load_lds_dwordx4 v162, s[98:99]
	s_mov_b32 m0, s56
	s_nop 0
	global_load_lds_dwordx4 v166, s[98:99]
	s_waitcnt vmcnt(8)
	s_waitcnt lgkmcnt(0)
	s_barrier
	s_setprio 1
	s_waitcnt lgkmcnt(0)
	v_mfma_scale_f32_16x16x128_f8f6f4 v[94:97], v[2:9], v[198:205], v[94:97], v1, v186 op_sel_hi:[0,0,0]
	v_mfma_scale_f32_16x16x128_f8f6f4 v[86:89], v[10:17], v[198:205], v[86:89], v1, v186 op_sel_hi:[0,0,0]
	v_mfma_scale_f32_16x16x128_f8f6f4 v[78:81], v[2:9], v[206:213], v[78:81], v1, v186 op_sel_hi:[0,0,0]
	v_mfma_scale_f32_16x16x128_f8f6f4 v[70:73], v[10:17], v[206:213], v[70:73], v1, v186 op_sel_hi:[0,0,0]
	v_mfma_scale_f32_16x16x128_f8f6f4 v[62:65], v[2:9], v[214:221], v[62:65], v1, v186 op_sel_hi:[0,0,0]
	v_mfma_scale_f32_16x16x128_f8f6f4 v[54:57], v[10:17], v[214:221], v[54:57], v1, v186 op_sel_hi:[0,0,0]
	v_mfma_scale_f32_16x16x128_f8f6f4 v[46:49], v[2:9], v[222:229], v[46:49], v1, v186 op_sel_hi:[0,0,0]
	v_mfma_scale_f32_16x16x128_f8f6f4 v[38:41], v[10:17], v[222:229], v[38:41], v1, v186 op_sel_hi:[0,0,0]
	s_setprio 0
	s_setprio 1
	v_mfma_scale_f32_16x16x128_f8f6f4 v[90:93], v[18:25], v[198:205], v[90:93], v1, v186 op_sel_hi:[0,0,0]
	v_mfma_scale_f32_16x16x128_f8f6f4 v[82:85], v[26:33], v[198:205], v[82:85], v1, v186 op_sel_hi:[0,0,0]
	v_mfma_scale_f32_16x16x128_f8f6f4 v[74:77], v[18:25], v[206:213], v[74:77], v1, v186 op_sel_hi:[0,0,0]
	v_mfma_scale_f32_16x16x128_f8f6f4 v[66:69], v[26:33], v[206:213], v[66:69], v1, v186 op_sel_hi:[0,0,0]
	v_mfma_scale_f32_16x16x128_f8f6f4 v[58:61], v[18:25], v[214:221], v[58:61], v1, v186 op_sel_hi:[0,0,0]
	v_mfma_scale_f32_16x16x128_f8f6f4 v[50:53], v[26:33], v[214:221], v[50:53], v1, v186 op_sel_hi:[0,0,0]
	v_mfma_scale_f32_16x16x128_f8f6f4 v[42:45], v[18:25], v[222:229], v[42:45], v1, v186 op_sel_hi:[0,0,0]
	v_mfma_scale_f32_16x16x128_f8f6f4 v[34:37], v[26:33], v[222:229], v[34:37], v1, v186 op_sel_hi:[0,0,0]
	s_setprio 0
	s_barrier
	s_add_i32 s65, s65, 2
	s_add_u32 s22, s22, 0x100
	s_addc_u32 s23, s23, 0
	s_add_u32 s63, s63, 0x100
	s_addc_u32 s64, s64, 0
	s_cmp_gt_u32 s65, 13
	s_cbranch_scc0 .LBB0_325
	s_and_b64 vcc, exec, s[10:11]
	s_cbranch_vccz .LBB0_328
	s_barrier

; #define PG8_STAGE(bufoff, gbase, voff) do { _Pragma("unroll") for (int _i = 0; _i < 2; ++_i) \
;         __builtin_amdgcn_global_load_lds((const unsigned*)((const char*)(gbase) + (voff)[_i]), (PG8_LAS unsigned*)(lds + (bufoff) + ldsw + _i * 8192), 16, 0, 0); } while (0)
; #define PG8_LDA(dst, b, h) do { _Pragma("unroll") for (int m = 0; m < 4; ++m) _Pragma("unroll") for (int k = 0; k < 2; ++k) dst[m][k] = *(const PG8_LAS bf16x8*)(lds + PG8_SA(b, h) + aoff + m * 2048 + k * 1024); } while (0)
; #define PG8_LDB(dst, b, h) do { _Pragma("unroll") for (int n = 0; n < 2; ++n) _Pragma("unroll") for (int k = 0; k < 2; ++k) dst[n][k] = *(const PG8_LAS bf16x8*)(lds + PG8_SB(b, h) + boff + n * 2048 + k * 1024); } while (0)
; #define PG8_WAIT_V(n) asm volatile("s_waitcnt vmcnt(" #n ")" ::: "memory")
; #define PG8_WAIT_L(n) asm volatile("s_waitcnt lgkmcnt(" #n ")" ::: "memory")
; template <class Epi, class Sched, bool ALIGN_EPI = false>
; __device__ __forceinline__ void gemm_phase8(PG8_LAS unsigned char* lds, const Gemm g, const Sched& S, const Epi& E) {
;     ...
;         const bool has_next = S.next(ui + 1, nxt);
;         const size_t nko = (has_next && nxt.kp > 0) ? (size_t)nxt.kp * g.kpiece : 0;
;         const char* nA = has_next ? (const char*)g.A + (size_t)nxt.pm * tstepA + (size_t)nxt.pn * astep + nko : cA; const char* nB = has_next ? (const char*)g.Bt + (size_t)nxt.pn * tstepB + nko : cB;
;         const int nt = (cur.kp < 0 ? g.K : g.kpiece) / 128;
;         for (int t = 0; t < nt; t += 2) {
;             const bool last = (t == nt - 2);
;             const char* a1 = cA + (size_t)(t + 1) * kstep;
;             const char* a2 = last ? nA : cA + (size_t)(t + 2) * kstep; const char* b2 = last ? nB : cB + (size_t)(t + 2) * kstep;
;             const char* a3 = a2 + kstep; const char* b3 = b2 + kstep;
;             if (last && has_next) S.a_ready(nxt);
;             PG8_LDB(B0, 0, 0); PG8_LDB(B1, 0, 1); PG8_SCHED; PG8_LDA(At, 0, 0); PG8_STAGE(PG8_SA(1, 1), a1 + hstepA, voffA);
;             PG8_WAIT_V(8); PG8_WAIT_L(0); PG8_BAR; PG8_MMA(0, 0, At, B0); PG8_MMA(0, 1, At, B1); PG8_BAR; PG8_SCHED;
;             PG8_LDA(At, 0, 1); PG8_STAGE(PG8_SB(0, 0), b2, voffB); PG8_STAGE(PG8_SB(0, 1), b2 + hstepB, voffB); PG8_STAGE(PG8_SA(0, 0), a2, voffA);
;             PG8_WAIT_V(8); PG8_WAIT_L(0); PG8_BAR; PG8_MMA(1, 0, At, B0); PG8_MMA(1, 1, At, B1); PG8_BAR; PG8_SCHED;
.LBB0_501:
	s_cmp_gt_i32 s24, -1
	s_cselect_b64 s[26:27], -1, 0
	s_cmp_lt_i32 s24, 0
	s_cselect_b32 s25, 44, 4
	s_add_i32 s81, s25, -2
	s_add_u32 s28, s28, 0xb0080
	s_addc_u32 s29, s29, 0
	s_add_u32 s82, s30, 0x100
	s_mov_b32 s34, 0
	s_addc_u32 s83, s31, 0
	ds_read_b128 v[18:21], v187
	ds_read_b128 v[26:29], v187 offset:2048
	ds_read_b128 v[22:25], v188
	ds_read_b128 v[30:33], v188 offset:2048
	ds_read_b128 v[2:5], v189
	ds_read_b128 v[10:13], v189 offset:2048
	ds_read_b128 v[6:9], v190
	ds_read_b128 v[14:17], v190 offset:2048
	s_add_i32 s84, s34, 2
	s_add_u32 s30, s28, 0xfff50080
	s_addc_u32 s31, s29, -1
	s_cmp_eq_u32 s81, s34
	s_cselect_b32 s34, s20, s30
	s_cselect_b32 s35, s21, s31
	s_cselect_b32 s31, s23, s83
	s_cselect_b32 s30, s22, s82
	s_add_i32 m0, s54, 0xc000
	ds_read_b128 v[174:177], v191
	ds_read_b128 v[194:197], v191 offset:2048
	ds_read_b128 v[178:181], v192
	ds_read_b128 v[198:201], v192 offset:2048
	ds_read_b128 v[202:205], v191 offset:4096
	ds_read_b128 v[210:213], v191 offset:6144
	ds_read_b128 v[206:209], v192 offset:4096
	ds_read_b128 v[214:217], v192 offset:6144
	global_load_lds_dwordx4 v170, s[28:29]
	s_add_i32 m0, s54, 0xe000
	s_nop 0
	global_load_lds_dwordx4 v172, s[28:29]
	s_waitcnt vmcnt(8)
	s_waitcnt lgkmcnt(0)
	s_barrier
	s_setprio 1
	s_waitcnt lgkmcnt(0)
	v_mfma_scale_f32_16x16x128_f8f6f4 v[158:161], v[18:25], v[174:181], 0, v1, v182 op_sel_hi:[0,0,0]
	v_mfma_scale_f32_16x16x128_f8f6f4 v[154:157], v[26:33], v[174:181], 0, v1, v182 op_sel_hi:[0,0,0]
	v_mfma_scale_f32_16x16x128_f8f6f4 v[142:145], v[18:25], v[194:201], 0, v1, v182 op_sel_hi:[0,0,0]
	v_mfma_scale_f32_16x16x128_f8f6f4 v[138:141], v[26:33], v[194:201], 0, v1, v182 op_sel_hi:[0,0,0]
	v_mfma_scale_f32_16x16x128_f8f6f4 v[126:129], v[18:25], v[202:209], 0, v1, v182 op_sel_hi:[0,0,0]
	v_mfma_scale_f32_16x16x128_f8f6f4 v[122:125], v[26:33], v[202:209], 0, v1, v182 op_sel_hi:[0,0,0]
	v_mfma_scale_f32_16x16x128_f8f6f4 v[110:113], v[18:25], v[210:217], 0, v1, v182 op_sel_hi:[0,0,0]
	v_mfma_scale_f32_16x16x128_f8f6f4 v[106:109], v[26:33], v[210:217], 0, v1, v182 op_sel_hi:[0,0,0]
	s_setprio 0
	s_setprio 1
	v_mfma_scale_f32_16x16x128_f8f6f4 v[150:153], v[2:9], v[174:181], 0, v1, v182 op_sel_hi:[0,0,0]
	v_mfma_scale_f32_16x16x128_f8f6f4 v[146:149], v[10:17], v[174:181], 0, v1, v182 op_sel_hi:[0,0,0]
	v_mfma_scale_f32_16x16x128_f8f6f4 v[134:137], v[2:9], v[194:201], 0, v1, v182 op_sel_hi:[0,0,0]
	v_mfma_scale_f32_16x16x128_f8f6f4 v[130:133], v[10:17], v[194:201], 0, v1, v182 op_sel_hi:[0,0,0]
	v_mfma_scale_f32_16x16x128_f8f6f4 v[118:121], v[2:9], v[202:209], 0, v1, v182 op_sel_hi:[0,0,0]
	v_mfma_scale_f32_16x16x128_f8f6f4 v[114:117], v[10:17], v[202:209], 0, v1, v182 op_sel_hi:[0,0,0]
	v_mfma_scale_f32_16x16x128_f8f6f4 v[102:105], v[2:9], v[210:217], 0, v1, v182 op_sel_hi:[0,0,0]
	v_mfma_scale_f32_16x16x128_f8f6f4 v[98:101], v[10:17], v[210:217], 0, v1, v182 op_sel_hi:[0,0,0]
	s_setprio 0
	s_barrier
	s_add_i32 s85, s65, s53
	s_mov_b32 m0, s85
	ds_read_b128 v[194:197], v191 offset:16384
	ds_read_b128 v[202:205], v191 offset:18432
	ds_read_b128 v[198:201], v192 offset:16384
	ds_read_b128 v[206:209], v192 offset:18432
	ds_read_b128 v[210:213], v191 offset:20480
	ds_read_b128 v[218:221], v191 offset:22528
	ds_read_b128 v[214:217], v192 offset:20480
	ds_read_b128 v[222:225], v192 offset:22528
	global_load_lds_dwordx4 v164, s[30:31]
	s_add_i32 m0, s85, 0x2000
	s_add_u32 s88, s30, 0xb0000
	s_addc_u32 s89, s31, 0
	s_add_i32 s85, s66, s53
	global_load_lds_dwordx4 v168, s[30:31]
	s_mov_b32 m0, s85
	s_nop 0
	global_load_lds_dwordx4 v164, s[88:89]
	s_add_i32 m0, s85, 0x2000
	s_nop 0
	global_load_lds_dwordx4 v168, s[88:89]
	s_mov_b32 m0, s54
	s_nop 0
	global_load_lds_dwordx4 v162, s[34:35]
	s_mov_b32 m0, s55
	s_nop 0
	global_load_lds_dwordx4 v166, s[34:35]
	s_waitcnt vmcnt(8)
	s_waitcnt lgkmcnt(0)
	s_barrier
	s_setprio 1
	s_waitcnt lgkmcnt(0)
	v_mfma_scale_f32_16x16x128_f8f6f4 v[94:97], v[18:25], v[194:201], 0, v1, v182 op_sel_hi:[0,0,0]
	v_mfma_scale_f32_16x16x128_f8f6f4 v[90:93], v[26:33], v[194:201], 0, v1, v182 op_sel_hi:[0,0,0]
	v_mfma_scale_f32_16x16x128_f8f6f4 v[78:81], v[18:25], v[202:209], 0, v1, v182 op_sel_hi:[0,0,0]
	v_mfma_scale_f32_16x16x128_f8f6f4 v[74:77], v[26:33], v[202:209], 0, v1, v182 op_sel_hi:[0,0,0]
	v_mfma_scale_f32_16x16x128_f8f6f4 v[62:65], v[18:25], v[210:217], 0, v1, v182 op_sel_hi:[0,0,0]
	v_mfma_scale_f32_16x16x128_f8f6f4 v[58:61], v[26:33], v[210:217], 0, v1, v182 op_sel_hi:[0,0,0]
	v_mfma_scale_f32_16x16x128_f8f6f4 v[46:49], v[18:25], v[218:225], 0, v1, v182 op_sel_hi:[0,0,0]
	v_mfma_scale_f32_16x16x128_f8f6f4 v[42:45], v[26:33], v[218:225], 0, v1, v182 op_sel_hi:[0,0,0]
	s_setprio 0
	s_setprio 1
	v_mfma_scale_f32_16x16x128_f8f6f4 v[86:89], v[2:9], v[194:201], 0, v1, v182 op_sel_hi:[0,0,0]
	v_mfma_scale_f32_16x16x128_f8f6f4 v[82:85], v[10:17], v[194:201], 0, v1, v182 op_sel_hi:[0,0,0]
	v_mfma_scale_f32_16x16x128_f8f6f4 v[70:73], v[2:9], v[202:209], 0, v1, v182 op_sel_hi:[0,0,0]
	v_mfma_scale_f32_16x16x128_f8f6f4 v[66:69], v[10:17], v[202:209], 0, v1, v182 op_sel_hi:[0,0,0]
	v_mfma_scale_f32_16x16x128_f8f6f4 v[54:57], v[2:9], v[210:217], 0, v1, v182 op_sel_hi:[0,0,0]
	v_mfma_scale_f32_16x16x128_f8f6f4 v[50:53], v[10:17], v[210:217], 0, v1, v182 op_sel_hi:[0,0,0]
	v_mfma_scale_f32_16x16x128_f8f6f4 v[38:41], v[2:9], v[218:225], 0, v1, v182 op_sel_hi:[0,0,0]
	v_mfma_scale_f32_16x16x128_f8f6f4 v[34:37], v[10:17], v[218:225], 0, v1, v182 op_sel_hi:[0,0,0]
	s_setprio 0
	s_barrier
	s_branch .Lmid_1

; #define PG8_STAGE(bufoff, gbase, voff) do { _Pragma("unroll") for (int _i = 0; _i < 2; ++_i) \
;         __builtin_amdgcn_global_load_lds((const unsigned*)((const char*)(gbase) + (voff)[_i]), (PG8_LAS unsigned*)(lds + (bufoff) + ldsw + _i * 8192), 16, 0, 0); } while (0)
; #define PG8_LDA(dst, b, h) do { _Pragma("unroll") for (int m = 0; m < 4; ++m) _Pragma("unroll") for (int k = 0; k < 2; ++k) dst[m][k] = *(const PG8_LAS bf16x8*)(lds + PG8_SA(b, h) + aoff + m * 2048 + k * 1024); } while (0)
; #define PG8_LDB(dst, b, h) do { _Pragma("unroll") for (int n = 0; n < 2; ++n) _Pragma("unroll") for (int k = 0; k < 2; ++k) dst[n][k] = *(const PG8_LAS bf16x8*)(lds + PG8_SB(b, h) + boff + n * 2048 + k * 1024); } while (0)
; #define PG8_MMA(ai, bj, At, Bt) do { __builtin_amdgcn_s_setprio(1); _Pragma("unroll") for (int m = 0; m < 4; ++m) _Pragma("unroll") for (int n = 0; n < 2; ++n) _Pragma("unroll") for (int k = 0; k < 2; ++k) \
;         acc[ai][bj][m][n] = __builtin_amdgcn_mfma_f32_16x16x32_bf16(Bt[n][k], At[m][k], acc[ai][bj][m][n], 0, 0, 0); __builtin_amdgcn_s_setprio(0); } while (0)
; #define PG8_WAIT_V(n) asm volatile("s_waitcnt vmcnt(" #n ")" ::: "memory")
; #define PG8_WAIT_L(n) asm volatile("s_waitcnt lgkmcnt(" #n ")" ::: "memory")
; #define PG8_BAR __builtin_amdgcn_s_barrier()
; #define PG8_SCHED __builtin_amdgcn_sched_barrier(0)
; #define PG8_STAGE(bufoff, gbase, voff) do { _Pragma("unroll") for (int _i = 0; _i < 2; ++_i) \
;         __builtin_amdgcn_global_load_lds((const unsigned*)((const char*)(gbase) + (voff)[_i]), (PG8_LAS unsigned*)(lds + (bufoff) + ldsw + _i * 8192), 16, 0, 0); } while (0)
; template <class Epi, class Sched, bool ALIGN_EPI = false>
; __device__ __forceinline__ void gemm_phase8(PG8_LAS unsigned char* lds, const Gemm g, const Sched& S, const Epi& E) {
;     ...
;             PG8_LDB(B0, 1, 0); PG8_LDB(B1, 1, 1); PG8_SCHED; PG8_LDA(At, 1, 0); PG8_STAGE(PG8_SA(0, 1), a2 + hstepA, voffA);
;             PG8_WAIT_V(8); PG8_WAIT_L(0); PG8_BAR; PG8_MMA(0, 0, At, B0); PG8_MMA(0, 1, At, B1); PG8_BAR; PG8_SCHED;
;             PG8_LDA(At, 1, 1); PG8_STAGE(PG8_SB(1, 0), b3, voffB); PG8_STAGE(PG8_SB(1, 1), b3 + hstepB, voffB); PG8_STAGE(PG8_SA(1, 0), a3, voffA);
;             PG8_WAIT_V(8); PG8_WAIT_L(0); PG8_BAR; PG8_MMA(1, 0, At, B0); PG8_MMA(1, 1, At, B1); PG8_BAR; PG8_SCHED;
;         }
;         if constexpr (ALIGN_EPI) { if (wr == 0) PG8_BAR; }
.Lmid_1:
	s_add_i32 s85, 0, 0x18000
	s_add_i32 s88, 0, 0x1c000
	v_add_u32_e32 v6, s85, v184
	v_add_u32_e32 v14, s85, v185
	v_add_u32_e32 v22, s88, v184
	v_add_u32_e32 v30, s88, v185
	ds_read_b128 v[2:5], v6
	ds_read_b128 v[10:13], v6 offset:2048
	ds_read_b128 v[6:9], v14
	ds_read_b128 v[14:17], v14 offset:2048
	ds_read_b128 v[18:21], v22
	ds_read_b128 v[26:29], v22 offset:2048
	ds_read_b128 v[22:25], v30
	ds_read_b128 v[30:33], v30 offset:2048
	s_add_u32 s34, s34, 0xb0000
	s_addc_u32 s35, s35, 0
	s_mov_b32 m0, s56
	ds_read_b128 v[194:197], v191 offset:32768
	ds_read_b128 v[202:205], v191 offset:34816
	ds_read_b128 v[198:201], v192 offset:32768
	ds_read_b128 v[206:209], v192 offset:34816
	ds_read_b128 v[210:213], v191 offset:36864
	ds_read_b128 v[218:221], v191 offset:38912
	ds_read_b128 v[214:217], v192 offset:36864
	ds_read_b128 v[222:225], v192 offset:38912
	global_load_lds_dwordx4 v162, s[34:35]
	s_mov_b32 m0, s57
	s_nop 0
	global_load_lds_dwordx4 v166, s[34:35]
	s_waitcnt vmcnt(8)
	s_waitcnt lgkmcnt(0)
	s_barrier
	s_setprio 1
	s_waitcnt lgkmcnt(0)
	v_mfma_scale_f32_16x16x128_f8f6f4 v[158:161], v[2:9], v[194:201], v[158:161], v1, v182 op_sel_hi:[0,0,0]
	v_mfma_scale_f32_16x16x128_f8f6f4 v[154:157], v[10:17], v[194:201], v[154:157], v1, v182 op_sel_hi:[0,0,0]
	v_mfma_scale_f32_16x16x128_f8f6f4 v[142:145], v[2:9], v[202:209], v[142:145], v1, v182 op_sel_hi:[0,0,0]
	v_mfma_scale_f32_16x16x128_f8f6f4 v[138:141], v[10:17], v[202:209], v[138:141], v1, v182 op_sel_hi:[0,0,0]
	v_mfma_scale_f32_16x16x128_f8f6f4 v[126:129], v[2:9], v[210:217], v[126:129], v1, v182 op_sel_hi:[0,0,0]
	v_mfma_scale_f32_16x16x128_f8f6f4 v[122:125], v[10:17], v[210:217], v[122:125], v1, v182 op_sel_hi:[0,0,0]
	v_mfma_scale_f32_16x16x128_f8f6f4 v[110:113], v[2:9], v[218:225], v[110:113], v1, v182 op_sel_hi:[0,0,0]
	v_mfma_scale_f32_16x16x128_f8f6f4 v[106:109], v[10:17], v[218:225], v[106:109], v1, v182 op_sel_hi:[0,0,0]
	s_setprio 0
	s_setprio 1
	v_mfma_scale_f32_16x16x128_f8f6f4 v[150:153], v[18:25], v[194:201], v[150:153], v1, v182 op_sel_hi:[0,0,0]
	v_mfma_scale_f32_16x16x128_f8f6f4 v[146:149], v[26:33], v[194:201], v[146:149], v1, v182 op_sel_hi:[0,0,0]
	v_mfma_scale_f32_16x16x128_f8f6f4 v[134:137], v[18:25], v[202:209], v[134:137], v1, v182 op_sel_hi:[0,0,0]
	v_mfma_scale_f32_16x16x128_f8f6f4 v[130:133], v[26:33], v[202:209], v[130:133], v1, v182 op_sel_hi:[0,0,0]
	v_mfma_scale_f32_16x16x128_f8f6f4 v[118:121], v[18:25], v[210:217], v[118:121], v1, v182 op_sel_hi:[0,0,0]
	v_mfma_scale_f32_16x16x128_f8f6f4 v[114:117], v[26:33], v[210:217], v[114:117], v1, v182 op_sel_hi:[0,0,0]
	v_mfma_scale_f32_16x16x128_f8f6f4 v[102:105], v[18:25], v[218:225], v[102:105], v1, v182 op_sel_hi:[0,0,0]
	v_mfma_scale_f32_16x16x128_f8f6f4 v[98:101], v[26:33], v[218:225], v[98:101], v1, v182 op_sel_hi:[0,0,0]
	s_setprio 0
	s_barrier
	s_add_i32 s101, s85, s53
	s_add_u32 s98, s30, s12
	s_addc_u32 s99, s31, s13
	s_mov_b32 m0, s101
	ds_read_b128 v[194:197], v191 offset:49152
	ds_read_b128 v[202:205], v191 offset:51200
	ds_read_b128 v[198:201], v192 offset:49152
	ds_read_b128 v[206:209], v192 offset:51200
	ds_read_b128 v[210:213], v191 offset:53248
	ds_read_b128 v[218:221], v191 offset:55296
	ds_read_b128 v[214:217], v192 offset:53248
	ds_read_b128 v[222:225], v192 offset:55296
	global_load_lds_dwordx4 v164, s[98:99]
	s_add_i32 m0, s101, 0x2000
	s_add_u32 s30, s30, 0xb0080
	s_addc_u32 s31, s31, 0
	s_add_i32 s101, s88, s53
	global_load_lds_dwordx4 v168, s[98:99]
	s_add_u32 s98, s34, s12
	s_addc_u32 s99, s35, s13
	s_sub_u32 s98, s98, 0xb0000
	s_subb_u32 s99, s99, 0
	s_mov_b32 m0, s101
	s_nop 0
	global_load_lds_dwordx4 v164, s[30:31]
	s_add_i32 m0, s101, 0x2000
	s_nop 0
	global_load_lds_dwordx4 v168, s[30:31]
	s_mov_b32 m0, s63
	s_nop 0
	global_load_lds_dwordx4 v162, s[98:99]
	s_mov_b32 m0, s64
	s_nop 0
	global_load_lds_dwordx4 v166, s[98:99]
	s_waitcnt vmcnt(8)
	s_waitcnt lgkmcnt(0)
	s_barrier
	s_setprio 1
	s_waitcnt lgkmcnt(0)
	v_mfma_scale_f32_16x16x128_f8f6f4 v[94:97], v[2:9], v[194:201], v[94:97], v1, v182 op_sel_hi:[0,0,0]
	v_mfma_scale_f32_16x16x128_f8f6f4 v[90:93], v[10:17], v[194:201], v[90:93], v1, v182 op_sel_hi:[0,0,0]
	v_mfma_scale_f32_16x16x128_f8f6f4 v[78:81], v[2:9], v[202:209], v[78:81], v1, v182 op_sel_hi:[0,0,0]
	v_mfma_scale_f32_16x16x128_f8f6f4 v[74:77], v[10:17], v[202:209], v[74:77], v1, v182 op_sel_hi:[0,0,0]
	v_mfma_scale_f32_16x16x128_f8f6f4 v[62:65], v[2:9], v[210:217], v[62:65], v1, v182 op_sel_hi:[0,0,0]
	v_mfma_scale_f32_16x16x128_f8f6f4 v[58:61], v[10:17], v[210:217], v[58:61], v1, v182 op_sel_hi:[0,0,0]
	v_mfma_scale_f32_16x16x128_f8f6f4 v[46:49], v[2:9], v[218:225], v[46:49], v1, v182 op_sel_hi:[0,0,0]
	v_mfma_scale_f32_16x16x128_f8f6f4 v[42:45], v[10:17], v[218:225], v[42:45], v1, v182 op_sel_hi:[0,0,0]
	s_setprio 0
	s_setprio 1
	v_mfma_scale_f32_16x16x128_f8f6f4 v[86:89], v[18:25], v[194:201], v[86:89], v1, v182 op_sel_hi:[0,0,0]
	v_mfma_scale_f32_16x16x128_f8f6f4 v[82:85], v[26:33], v[194:201], v[82:85], v1, v182 op_sel_hi:[0,0,0]
	v_mfma_scale_f32_16x16x128_f8f6f4 v[70:73], v[18:25], v[202:209], v[70:73], v1, v182 op_sel_hi:[0,0,0]
	v_mfma_scale_f32_16x16x128_f8f6f4 v[66:69], v[26:33], v[202:209], v[66:69], v1, v182 op_sel_hi:[0,0,0]
	v_mfma_scale_f32_16x16x128_f8f6f4 v[54:57], v[18:25], v[210:217], v[54:57], v1, v182 op_sel_hi:[0,0,0]
	v_mfma_scale_f32_16x16x128_f8f6f4 v[50:53], v[26:33], v[210:217], v[50:53], v1, v182 op_sel_hi:[0,0,0]
	v_mfma_scale_f32_16x16x128_f8f6f4 v[38:41], v[18:25], v[218:225], v[38:41], v1, v182 op_sel_hi:[0,0,0]
	v_mfma_scale_f32_16x16x128_f8f6f4 v[34:37], v[26:33], v[218:225], v[34:37], v1, v182 op_sel_hi:[0,0,0]
	s_setprio 0
	s_barrier
	s_add_u32 s28, s28, 0x100
	s_addc_u32 s29, s29, 0
	s_add_u32 s82, s82, 0x100
	s_addc_u32 s83, s83, 0
	s_cmp_ge_u32 s84, s25
	s_mov_b32 s34, s84
	s_cbranch_scc0 .LBB0_502
	s_and_b64 vcc, exec, s[14:15]
	s_cbranch_vccz .LBB0_505
	s_barrier

; #define PG8_STAGE(bufoff, gbase, voff) do { _Pragma("unroll") for (int _i = 0; _i < 2; ++_i) \
;         __builtin_amdgcn_global_load_lds((const unsigned*)((const char*)(gbase) + (voff)[_i]), (PG8_LAS unsigned*)(lds + (bufoff) + ldsw + _i * 8192), 16, 0, 0); } while (0)
; #define PG8_LDA(dst, b, h) do { _Pragma("unroll") for (int m = 0; m < 4; ++m) _Pragma("unroll") for (int k = 0; k < 2; ++k) dst[m][k] = *(const PG8_LAS bf16x8*)(lds + PG8_SA(b, h) + aoff + m * 2048 + k * 1024); } while (0)
; #define PG8_LDB(dst, b, h) do { _Pragma("unroll") for (int n = 0; n < 2; ++n) _Pragma("unroll") for (int k = 0; k < 2; ++k) dst[n][k] = *(const PG8_LAS bf16x8*)(lds + PG8_SB(b, h) + boff + n * 2048 + k * 1024); } while (0)
; #define PG8_MMA(ai, bj, At, Bt) do { __builtin_amdgcn_s_setprio(1); _Pragma("unroll") for (int m = 0; m < 4; ++m) _Pragma("unroll") for (int n = 0; n < 2; ++n) _Pragma("unroll") for (int k = 0; k < 2; ++k) \
;         acc[ai][bj][m][n] = __builtin_amdgcn_mfma_f32_16x16x32_bf16(Bt[n][k], At[m][k], acc[ai][bj][m][n], 0, 0, 0); __builtin_amdgcn_s_setprio(0); } while (0)
; template <class Epi, class Sched, bool ALIGN_EPI = false>
; __device__ __forceinline__ void gemm_phase(PG8_LAS unsigned char* lds, const Gemm g, const Sched& S, const Epi& E) {
;     ...
;     PG8_WAIT_V(6); PG8_BAR;
;     for (;;) {
;         const bool has_next = S.next(ui + 1, nxt);
;         const size_t nko = (has_next && nxt.kp > 0) ? (size_t)nxt.kp * g.kpiece * 2 : 0;
;         const char* nA = has_next ? (const char*)g.A + (size_t)nxt.pm * tstepA + (size_t)nxt.pn * astep + nko : cA; const char* nB = has_next ? (const char*)g.Bt + (size_t)nxt.pn * tstepB + nko : cB;
;         const int nt = (cur.kp < 0 ? g.K : g.kpiece) / BK;
;         for (int t = 0; t < nt; t += 2) {
;             const bool last = (t == nt - 2);
;             const char* a1 = cA + (size_t)(t + 1) * kstep;
;             const char* a2 = last ? nA : cA + (size_t)(t + 2) * kstep; const char* b2 = last ? nB : cB + (size_t)(t + 2) * kstep;
;             const char* a3 = a2 + kstep; const char* b3 = b2 + kstep;
;             if (last && has_next) S.a_ready(nxt);
;             PG8_LDB(B0, 0, 0); PG8_LDB(B1, 0, 1); PG8_SCHED; PG8_LDA(At, 0, 0); PG8_STAGE(PG8_SA(1, 1), a1 + hstepA, voffA);
;             PG8_WAIT_V(8); PG8_WAIT_L(0); PG8_BAR; PG8_MMA(0, 0, At, B0); PG8_MMA(0, 1, At, B1); PG8_BAR; PG8_SCHED;
.LBB0_733:
	s_ashr_i32 s27, s26, 31
	s_lshl_b64 s[28:29], s[26:27], 20
	s_add_u32 s28, s56, s28
	s_addc_u32 s29, s57, s29
	s_and_b64 s[30:31], s[2:3], exec
	s_cselect_b32 s13, s29, s53
	s_cselect_b32 s27, s28, s52
	s_ashr_i32 s25, s24, 31
	s_lshl_b64 s[30:31], s[24:25], 20
	s_add_u32 s30, s4, s30
	s_addc_u32 s31, s5, s31
	s_and_b64 s[54:55], s[2:3], exec
	s_cselect_b32 s25, s31, s35
	s_cselect_b32 s82, s30, s34
	s_add_u32 s52, s52, 0x80080
	s_addc_u32 s53, s53, 0
	s_add_u32 s83, s34, 0x100
	s_addc_u32 s84, s35, 0
	s_mov_b32 s85, -2
	ds_read_b128 v[130:133], v165
	ds_read_b128 v[134:137], v165 offset:1024
	ds_read_b128 v[158:161], v165 offset:2048
	ds_read_b128 v[170:173], v165 offset:3072
	ds_read_b128 v[174:177], v166
	ds_read_b128 v[178:181], v166 offset:1024
	ds_read_b128 v[182:185], v166 offset:2048
	ds_read_b128 v[186:189], v166 offset:3072
	s_add_u32 s34, s52, 0xfff80080
	s_addc_u32 s35, s53, -1
	s_cmp_eq_u32 s85, 28
	s_cselect_b32 s55, s13, s35
	s_cselect_b32 s54, s27, s34
	s_cselect_b32 s35, s25, s84
	s_cselect_b32 s34, s82, s83
	s_add_i32 m0, s61, 0xc000
	ds_read_b128 v[190:193], v167
	ds_read_b128 v[194:197], v167 offset:1024
	ds_read_b128 v[198:201], v167 offset:2048
	ds_read_b128 v[202:205], v167 offset:3072
	ds_read_b128 v[206:209], v167 offset:4096
	ds_read_b128 v[210:213], v167 offset:5120
	ds_read_b128 v[214:217], v167 offset:6144
	ds_read_b128 v[218:221], v167 offset:7168
	global_load_lds_dwordx4 v150, s[52:53]
	s_add_i32 m0, s61, 0xe000
	s_nop 0
	global_load_lds_dwordx4 v152, s[52:53]
	s_waitcnt vmcnt(8)
	s_waitcnt lgkmcnt(0)
	s_barrier
	s_waitcnt lgkmcnt(0)
	v_mfma_f32_16x16x32_bf16 v[126:129], v[130:133], v[190:193], 0
	v_mfma_f32_16x16x32_bf16 v[122:125], v[158:161], v[190:193], 0
	v_mfma_f32_16x16x32_bf16 v[114:117], v[130:133], v[198:201], 0
	v_mfma_f32_16x16x32_bf16 v[106:109], v[158:161], v[198:201], 0
	v_mfma_f32_16x16x32_bf16 v[98:101], v[130:133], v[206:209], 0
	v_mfma_f32_16x16x32_bf16 v[90:93], v[158:161], v[206:209], 0
	v_mfma_f32_16x16x32_bf16 v[82:85], v[130:133], v[214:217], 0
	v_mfma_f32_16x16x32_bf16 v[74:77], v[158:161], v[214:217], 0
	v_mfma_f32_16x16x32_bf16 v[126:129], v[134:137], v[194:197], v[126:129]
	v_mfma_f32_16x16x32_bf16 v[122:125], v[170:173], v[194:197], v[122:125]
	v_mfma_f32_16x16x32_bf16 v[114:117], v[134:137], v[202:205], v[114:117]
	v_mfma_f32_16x16x32_bf16 v[106:109], v[170:173], v[202:205], v[106:109]
	v_mfma_f32_16x16x32_bf16 v[98:101], v[134:137], v[210:213], v[98:101]
	v_mfma_f32_16x16x32_bf16 v[90:93], v[170:173], v[210:213], v[90:93]
	v_mfma_f32_16x16x32_bf16 v[82:85], v[134:137], v[218:221], v[82:85]
	v_mfma_f32_16x16x32_bf16 v[74:77], v[170:173], v[218:221], v[74:77]
	v_mfma_f32_16x16x32_bf16 v[118:121], v[174:177], v[190:193], 0
	v_mfma_f32_16x16x32_bf16 v[110:113], v[182:185], v[190:193], 0
	v_mfma_f32_16x16x32_bf16 v[102:105], v[174:177], v[198:201], 0
	v_mfma_f32_16x16x32_bf16 v[94:97], v[182:185], v[198:201], 0
	v_mfma_f32_16x16x32_bf16 v[86:89], v[174:177], v[206:209], 0
	v_mfma_f32_16x16x32_bf16 v[78:81], v[182:185], v[206:209], 0
	v_mfma_f32_16x16x32_bf16 v[70:73], v[174:177], v[214:217], 0
	v_mfma_f32_16x16x32_bf16 v[66:69], v[182:185], v[214:217], 0
	v_mfma_f32_16x16x32_bf16 v[118:121], v[178:181], v[194:197], v[118:121]
	v_mfma_f32_16x16x32_bf16 v[110:113], v[186:189], v[194:197], v[110:113]
	v_mfma_f32_16x16x32_bf16 v[102:105], v[178:181], v[202:205], v[102:105]
	v_mfma_f32_16x16x32_bf16 v[94:97], v[186:189], v[202:205], v[94:97]
	v_mfma_f32_16x16x32_bf16 v[86:89], v[178:181], v[210:213], v[86:89]
	v_mfma_f32_16x16x32_bf16 v[78:81], v[186:189], v[210:213], v[78:81]
	v_mfma_f32_16x16x32_bf16 v[70:73], v[178:181], v[218:221], v[70:73]
	v_mfma_f32_16x16x32_bf16 v[66:69], v[186:189], v[218:221], v[66:69]
	s_barrier
	s_add_i32 s88, s72, s58
	s_mov_b32 m0, s88
	ds_read_b128 v[190:193], v167 offset:16384
	ds_read_b128 v[194:197], v167 offset:17408
	ds_read_b128 v[198:201], v167 offset:18432
	ds_read_b128 v[202:205], v167 offset:19456
	ds_read_b128 v[206:209], v167 offset:20480
	ds_read_b128 v[210:213], v167 offset:21504
	ds_read_b128 v[214:217], v167 offset:22528
	ds_read_b128 v[218:221], v167 offset:23552
	global_load_lds_dwordx4 v140, s[34:35]
	s_add_i32 m0, s88, 0x2000
	s_add_u32 s88, s34, 0x80000
	s_addc_u32 s89, s35, 0
	s_add_i32 s90, s73, s58
	global_load_lds_dwordx4 v144, s[34:35]
	s_mov_b32 m0, s90
	s_nop 0
	global_load_lds_dwordx4 v140, s[88:89]
	s_add_i32 m0, s90, 0x2000
	s_nop 0
	global_load_lds_dwordx4 v144, s[88:89]
	s_mov_b32 m0, s61
	s_nop 0
	global_load_lds_dwordx4 v138, s[54:55]
	s_mov_b32 m0, s62
	s_nop 0
	global_load_lds_dwordx4 v142, s[54:55]
	s_waitcnt vmcnt(8)
	s_waitcnt lgkmcnt(0)
	s_barrier
	s_waitcnt lgkmcnt(0)
	v_mfma_f32_16x16x32_bf16 v[62:65], v[130:133], v[190:193], 0
	v_mfma_f32_16x16x32_bf16 v[58:61], v[158:161], v[190:193], 0
	v_mfma_f32_16x16x32_bf16 v[54:57], v[130:133], v[198:201], 0
	v_mfma_f32_16x16x32_bf16 v[46:49], v[158:161], v[198:201], 0
	v_mfma_f32_16x16x32_bf16 v[38:41], v[130:133], v[206:209], 0
	v_mfma_f32_16x16x32_bf16 v[30:33], v[158:161], v[206:209], 0
	v_mfma_f32_16x16x32_bf16 v[22:25], v[130:133], v[214:217], 0
	v_mfma_f32_16x16x32_bf16 v[14:17], v[158:161], v[214:217], 0
	v_mfma_f32_16x16x32_bf16 v[62:65], v[134:137], v[194:197], v[62:65]
	v_mfma_f32_16x16x32_bf16 v[58:61], v[170:173], v[194:197], v[58:61]
	v_mfma_f32_16x16x32_bf16 v[54:57], v[134:137], v[202:205], v[54:57]
	v_mfma_f32_16x16x32_bf16 v[46:49], v[170:173], v[202:205], v[46:49]
	v_mfma_f32_16x16x32_bf16 v[38:41], v[134:137], v[210:213], v[38:41]
	v_mfma_f32_16x16x32_bf16 v[30:33], v[170:173], v[210:213], v[30:33]
	v_mfma_f32_16x16x32_bf16 v[22:25], v[134:137], v[218:221], v[22:25]
	v_mfma_f32_16x16x32_bf16 v[14:17], v[170:173], v[218:221], v[14:17]
	v_mfma_f32_16x16x32_bf16 v[50:53], v[174:177], v[190:193], 0
	v_mfma_f32_16x16x32_bf16 v[42:45], v[182:185], v[190:193], 0
	v_mfma_f32_16x16x32_bf16 v[34:37], v[174:177], v[198:201], 0
	v_mfma_f32_16x16x32_bf16 v[26:29], v[182:185], v[198:201], 0
	v_mfma_f32_16x16x32_bf16 v[18:21], v[174:177], v[206:209], 0
	v_mfma_f32_16x16x32_bf16 v[10:13], v[182:185], v[206:209], 0
	v_mfma_f32_16x16x32_bf16 v[6:9], v[174:177], v[214:217], 0
	v_mfma_f32_16x16x32_bf16 v[2:5], v[182:185], v[214:217], 0
	v_mfma_f32_16x16x32_bf16 v[50:53], v[178:181], v[194:197], v[50:53]
	v_mfma_f32_16x16x32_bf16 v[42:45], v[186:189], v[194:197], v[42:45]
	v_mfma_f32_16x16x32_bf16 v[34:37], v[178:181], v[202:205], v[34:37]
	v_mfma_f32_16x16x32_bf16 v[26:29], v[186:189], v[202:205], v[26:29]
	v_mfma_f32_16x16x32_bf16 v[18:21], v[178:181], v[210:213], v[18:21]
	v_mfma_f32_16x16x32_bf16 v[10:13], v[186:189], v[210:213], v[10:13]
	v_mfma_f32_16x16x32_bf16 v[6:9], v[178:181], v[218:221], v[6:9]
	v_mfma_f32_16x16x32_bf16 v[2:5], v[186:189], v[218:221], v[2:5]
	s_barrier
	s_branch .Lmid_2

; #define PG8_STAGE(bufoff, gbase, voff) do { _Pragma("unroll") for (int _i = 0; _i < 2; ++_i) \
;         __builtin_amdgcn_global_load_lds((const unsigned*)((const char*)(gbase) + (voff)[_i]), (PG8_LAS unsigned*)(lds + (bufoff) + ldsw + _i * 8192), 16, 0, 0); } while (0)
; #define PG8_LDA(dst, b, h) do { _Pragma("unroll") for (int m = 0; m < 4; ++m) _Pragma("unroll") for (int k = 0; k < 2; ++k) dst[m][k] = *(const PG8_LAS bf16x8*)(lds + PG8_SA(b, h) + aoff + m * 2048 + k * 1024); } while (0)
; #define PG8_LDB(dst, b, h) do { _Pragma("unroll") for (int n = 0; n < 2; ++n) _Pragma("unroll") for (int k = 0; k < 2; ++k) dst[n][k] = *(const PG8_LAS bf16x8*)(lds + PG8_SB(b, h) + boff + n * 2048 + k * 1024); } while (0)
; #define PG8_MMA(ai, bj, At, Bt) do { __builtin_amdgcn_s_setprio(1); _Pragma("unroll") for (int m = 0; m < 4; ++m) _Pragma("unroll") for (int n = 0; n < 2; ++n) _Pragma("unroll") for (int k = 0; k < 2; ++k) \
;         acc[ai][bj][m][n] = __builtin_amdgcn_mfma_f32_16x16x32_bf16(Bt[n][k], At[m][k], acc[ai][bj][m][n], 0, 0, 0); __builtin_amdgcn_s_setprio(0); } while (0)
; #define PG8_WAIT_V(n) asm volatile("s_waitcnt vmcnt(" #n ")" ::: "memory")
; #define PG8_WAIT_L(n) asm volatile("s_waitcnt lgkmcnt(" #n ")" ::: "memory")
; #define PG8_BAR __builtin_amdgcn_s_barrier()
; #define PG8_SCHED __builtin_amdgcn_sched_barrier(0)
; template <class Epi, class Sched, bool ALIGN_EPI = false>
; __device__ __forceinline__ void gemm_phase(PG8_LAS unsigned char* lds, const Gemm g, const Sched& S, const Epi& E) {
;     ...
;             PG8_LDA(At, 0, 1); PG8_STAGE(PG8_SB(0, 0), b2, voffB); PG8_STAGE(PG8_SB(0, 1), b2 + hstepB, voffB); PG8_STAGE(PG8_SA(0, 0), a2, voffA);
;             PG8_WAIT_V(8); PG8_WAIT_L(0); PG8_BAR; PG8_MMA(1, 0, At, B0); PG8_MMA(1, 1, At, B1); PG8_BAR; PG8_SCHED;
;             PG8_LDB(B0, 1, 0); PG8_LDB(B1, 1, 1); PG8_SCHED; PG8_LDA(At, 1, 0); PG8_STAGE(PG8_SA(0, 1), a2 + hstepA, voffA);
;             PG8_WAIT_V(8); PG8_WAIT_L(0); PG8_BAR; PG8_MMA(0, 0, At, B0); PG8_MMA(0, 1, At, B1); PG8_BAR; PG8_SCHED;
;             PG8_LDA(At, 1, 1); PG8_STAGE(PG8_SB(1, 0), b3, voffB); PG8_STAGE(PG8_SB(1, 1), b3 + hstepB, voffB); PG8_STAGE(PG8_SA(1, 0), a3, voffA);
;             PG8_WAIT_V(8); PG8_WAIT_L(0); PG8_BAR; PG8_MMA(1, 0, At, B0); PG8_MMA(1, 1, At, B1); PG8_BAR; PG8_SCHED;
;         }
;         if constexpr (ALIGN_EPI) { if (wr == 0) PG8_BAR; }
.Lmid_2:
	s_add_i32 s88, 0, 0x18000
	v_add_u32_e32 v146, s88, v164
	s_add_i32 s89, 0, 0x1c000
	ds_read_b128 v[130:133], v146
	ds_read_b128 v[134:137], v146 offset:1024
	ds_read_b128 v[158:161], v146 offset:2048
	ds_read_b128 v[170:173], v146 offset:3072
	v_add_u32_e32 v146, s89, v164
	ds_read_b128 v[174:177], v146
	ds_read_b128 v[178:181], v146 offset:1024
	ds_read_b128 v[182:185], v146 offset:2048
	ds_read_b128 v[186:189], v146 offset:3072
	s_add_u32 s54, s54, 0x80000
	s_addc_u32 s55, s55, 0
	s_mov_b32 m0, s63
	ds_read_b128 v[190:193], v167 offset:32768
	ds_read_b128 v[194:197], v167 offset:33792
	ds_read_b128 v[198:201], v167 offset:34816
	ds_read_b128 v[202:205], v167 offset:35840
	ds_read_b128 v[206:209], v167 offset:36864
	ds_read_b128 v[210:213], v167 offset:37888
	ds_read_b128 v[214:217], v167 offset:38912
	ds_read_b128 v[218:221], v167 offset:39936
	global_load_lds_dwordx4 v138, s[54:55]
	s_mov_b32 m0, s64
	s_nop 0
	global_load_lds_dwordx4 v142, s[54:55]
	s_waitcnt vmcnt(8)
	s_waitcnt lgkmcnt(0)
	s_barrier
	s_waitcnt lgkmcnt(0)
	v_mfma_f32_16x16x32_bf16 v[126:129], v[130:133], v[190:193], v[126:129]
	v_mfma_f32_16x16x32_bf16 v[122:125], v[158:161], v[190:193], v[122:125]
	v_mfma_f32_16x16x32_bf16 v[114:117], v[130:133], v[198:201], v[114:117]
	v_mfma_f32_16x16x32_bf16 v[106:109], v[158:161], v[198:201], v[106:109]
	v_mfma_f32_16x16x32_bf16 v[98:101], v[130:133], v[206:209], v[98:101]
	v_mfma_f32_16x16x32_bf16 v[90:93], v[158:161], v[206:209], v[90:93]
	v_mfma_f32_16x16x32_bf16 v[82:85], v[130:133], v[214:217], v[82:85]
	v_mfma_f32_16x16x32_bf16 v[74:77], v[158:161], v[214:217], v[74:77]
	v_mfma_f32_16x16x32_bf16 v[126:129], v[134:137], v[194:197], v[126:129]
	v_mfma_f32_16x16x32_bf16 v[122:125], v[170:173], v[194:197], v[122:125]
	v_mfma_f32_16x16x32_bf16 v[114:117], v[134:137], v[202:205], v[114:117]
	v_mfma_f32_16x16x32_bf16 v[106:109], v[170:173], v[202:205], v[106:109]
	v_mfma_f32_16x16x32_bf16 v[98:101], v[134:137], v[210:213], v[98:101]
	v_mfma_f32_16x16x32_bf16 v[90:93], v[170:173], v[210:213], v[90:93]
	v_mfma_f32_16x16x32_bf16 v[82:85], v[134:137], v[218:221], v[82:85]
	v_mfma_f32_16x16x32_bf16 v[74:77], v[170:173], v[218:221], v[74:77]
	v_mfma_f32_16x16x32_bf16 v[118:121], v[174:177], v[190:193], v[118:121]
	v_mfma_f32_16x16x32_bf16 v[110:113], v[182:185], v[190:193], v[110:113]
	v_mfma_f32_16x16x32_bf16 v[102:105], v[174:177], v[198:201], v[102:105]
	v_mfma_f32_16x16x32_bf16 v[94:97], v[182:185], v[198:201], v[94:97]
	v_mfma_f32_16x16x32_bf16 v[86:89], v[174:177], v[206:209], v[86:89]
	v_mfma_f32_16x16x32_bf16 v[78:81], v[182:185], v[206:209], v[78:81]
	v_mfma_f32_16x16x32_bf16 v[70:73], v[174:177], v[214:217], v[70:73]
	v_mfma_f32_16x16x32_bf16 v[66:69], v[182:185], v[214:217], v[66:69]
	v_mfma_f32_16x16x32_bf16 v[118:121], v[178:181], v[194:197], v[118:121]
	v_mfma_f32_16x16x32_bf16 v[110:113], v[186:189], v[194:197], v[110:113]
	v_mfma_f32_16x16x32_bf16 v[102:105], v[178:181], v[202:205], v[102:105]
	v_mfma_f32_16x16x32_bf16 v[94:97], v[186:189], v[202:205], v[94:97]
	v_mfma_f32_16x16x32_bf16 v[86:89], v[178:181], v[210:213], v[86:89]
	v_mfma_f32_16x16x32_bf16 v[78:81], v[186:189], v[210:213], v[78:81]
	v_mfma_f32_16x16x32_bf16 v[70:73], v[178:181], v[218:221], v[70:73]
	v_mfma_f32_16x16x32_bf16 v[66:69], v[186:189], v[218:221], v[66:69]
	s_barrier
	s_add_i32 s101, s88, s58
	s_add_u32 s98, s34, s10
	s_addc_u32 s99, s35, s11
	s_mov_b32 m0, s101
	ds_read_b128 v[190:193], v167 offset:49152
	ds_read_b128 v[194:197], v167 offset:50176
	ds_read_b128 v[198:201], v167 offset:51200
	ds_read_b128 v[202:205], v167 offset:52224
	ds_read_b128 v[206:209], v167 offset:53248
	ds_read_b128 v[210:213], v167 offset:54272
	ds_read_b128 v[214:217], v167 offset:55296
	ds_read_b128 v[218:221], v167 offset:56320
	global_load_lds_dwordx4 v140, s[98:99]
	s_add_i32 m0, s101, 0x2000
	s_add_u32 s34, s34, 0x80080
	s_addc_u32 s35, s35, 0
	s_add_i32 s101, s89, s58
	global_load_lds_dwordx4 v144, s[98:99]
	s_add_u32 s98, s54, s10
	s_addc_u32 s99, s55, s11
	s_sub_u32 s98, s98, 0x80000
	s_subb_u32 s99, s99, 0
	s_mov_b32 m0, s101
	s_nop 0
	global_load_lds_dwordx4 v140, s[34:35]
	s_add_i32 m0, s101, 0x2000
	s_nop 0
	global_load_lds_dwordx4 v144, s[34:35]
	s_mov_b32 m0, s70
	s_nop 0
	global_load_lds_dwordx4 v138, s[98:99]
	s_mov_b32 m0, s71
	s_nop 0
	global_load_lds_dwordx4 v142, s[98:99]
	s_waitcnt vmcnt(8)
	s_waitcnt lgkmcnt(0)
	s_barrier
	s_waitcnt lgkmcnt(0)
	v_mfma_f32_16x16x32_bf16 v[62:65], v[130:133], v[190:193], v[62:65]
	v_mfma_f32_16x16x32_bf16 v[58:61], v[158:161], v[190:193], v[58:61]
	v_mfma_f32_16x16x32_bf16 v[54:57], v[130:133], v[198:201], v[54:57]
	v_mfma_f32_16x16x32_bf16 v[46:49], v[158:161], v[198:201], v[46:49]
	v_mfma_f32_16x16x32_bf16 v[38:41], v[130:133], v[206:209], v[38:41]
	v_mfma_f32_16x16x32_bf16 v[30:33], v[158:161], v[206:209], v[30:33]
	v_mfma_f32_16x16x32_bf16 v[22:25], v[130:133], v[214:217], v[22:25]
	v_mfma_f32_16x16x32_bf16 v[14:17], v[158:161], v[214:217], v[14:17]
	v_mfma_f32_16x16x32_bf16 v[62:65], v[134:137], v[194:197], v[62:65]
	v_mfma_f32_16x16x32_bf16 v[58:61], v[170:173], v[194:197], v[58:61]
	v_mfma_f32_16x16x32_bf16 v[54:57], v[134:137], v[202:205], v[54:57]
	v_mfma_f32_16x16x32_bf16 v[46:49], v[170:173], v[202:205], v[46:49]
	v_mfma_f32_16x16x32_bf16 v[38:41], v[134:137], v[210:213], v[38:41]
	v_mfma_f32_16x16x32_bf16 v[30:33], v[170:173], v[210:213], v[30:33]
	v_mfma_f32_16x16x32_bf16 v[22:25], v[134:137], v[218:221], v[22:25]
	v_mfma_f32_16x16x32_bf16 v[14:17], v[170:173], v[218:221], v[14:17]
	v_mfma_f32_16x16x32_bf16 v[50:53], v[174:177], v[190:193], v[50:53]
	v_mfma_f32_16x16x32_bf16 v[42:45], v[182:185], v[190:193], v[42:45]
	v_mfma_f32_16x16x32_bf16 v[34:37], v[174:177], v[198:201], v[34:37]
	v_mfma_f32_16x16x32_bf16 v[26:29], v[182:185], v[198:201], v[26:29]
	v_mfma_f32_16x16x32_bf16 v[18:21], v[174:177], v[206:209], v[18:21]
	v_mfma_f32_16x16x32_bf16 v[10:13], v[182:185], v[206:209], v[10:13]
	v_mfma_f32_16x16x32_bf16 v[6:9], v[174:177], v[214:217], v[6:9]
	v_mfma_f32_16x16x32_bf16 v[2:5], v[182:185], v[214:217], v[2:5]
	v_mfma_f32_16x16x32_bf16 v[50:53], v[178:181], v[194:197], v[50:53]
	v_mfma_f32_16x16x32_bf16 v[42:45], v[186:189], v[194:197], v[42:45]
	v_mfma_f32_16x16x32_bf16 v[34:37], v[178:181], v[202:205], v[34:37]
	v_mfma_f32_16x16x32_bf16 v[26:29], v[186:189], v[202:205], v[26:29]
	v_mfma_f32_16x16x32_bf16 v[18:21], v[178:181], v[210:213], v[18:21]
	v_mfma_f32_16x16x32_bf16 v[10:13], v[186:189], v[210:213], v[10:13]
	v_mfma_f32_16x16x32_bf16 v[6:9], v[178:181], v[218:221], v[6:9]
	v_mfma_f32_16x16x32_bf16 v[2:5], v[186:189], v[218:221], v[2:5]
	s_barrier
	s_add_i32 s85, s85, 2
	s_add_u32 s52, s52, 0x100
	s_addc_u32 s53, s53, 0
	s_add_u32 s83, s83, 0x100
	s_addc_u32 s84, s84, 0
	s_cmp_gt_u32 s85, 29
	s_cbranch_scc0 .LBB0_734
	s_and_b64 vcc, exec, s[14:15]
	s_cbranch_vccz .LBB0_737
	s_barrier

; #define PG8_STAGE(bufoff, gbase, voff) do { _Pragma("unroll") for (int _i = 0; _i < 2; ++_i) \
;         __builtin_amdgcn_global_load_lds((const unsigned*)((const char*)(gbase) + (voff)[_i]), (PG8_LAS unsigned*)(lds + (bufoff) + ldsw + _i * 8192), 16, 0, 0); } while (0)
; #define PG8_LDA(dst, b, h) do { _Pragma("unroll") for (int m = 0; m < 4; ++m) _Pragma("unroll") for (int k = 0; k < 2; ++k) dst[m][k] = *(const PG8_LAS bf16x8*)(lds + PG8_SA(b, h) + aoff + m * 2048 + k * 1024); } while (0)
; #define PG8_LDB(dst, b, h) do { _Pragma("unroll") for (int n = 0; n < 2; ++n) _Pragma("unroll") for (int k = 0; k < 2; ++k) dst[n][k] = *(const PG8_LAS bf16x8*)(lds + PG8_SB(b, h) + boff + n * 2048 + k * 1024); } while (0)
; #define PG8_WAIT_V(n) asm volatile("s_waitcnt vmcnt(" #n ")" ::: "memory")
; #define PG8_WAIT_L(n) asm volatile("s_waitcnt lgkmcnt(" #n ")" ::: "memory")
; template <class Epi, class Sched, bool ALIGN_EPI = false>
; __device__ __forceinline__ void gemm_phase8(PG8_LAS unsigned char* lds, const Gemm g, const Sched& S, const Epi& E) {
;     ...
;         const bool has_next = S.next(ui + 1, nxt);
;         const size_t nko = (has_next && nxt.kp > 0) ? (size_t)nxt.kp * g.kpiece : 0;
;         const char* nA = has_next ? (const char*)g.A + (size_t)nxt.pm * tstepA + (size_t)nxt.pn * astep + nko : cA; const char* nB = has_next ? (const char*)g.Bt + (size_t)nxt.pn * tstepB + nko : cB;
;         const int nt = (cur.kp < 0 ? g.K : g.kpiece) / 128;
;         for (int t = 0; t < nt; t += 2) {
;             const bool last = (t == nt - 2);
;             const char* a1 = cA + (size_t)(t + 1) * kstep;
;             const char* a2 = last ? nA : cA + (size_t)(t + 2) * kstep; const char* b2 = last ? nB : cB + (size_t)(t + 2) * kstep;
;             const char* a3 = a2 + kstep; const char* b3 = b2 + kstep;
;             if (last && has_next) S.a_ready(nxt);
;             PG8_LDB(B0, 0, 0); PG8_LDB(B1, 0, 1); PG8_SCHED; PG8_LDA(At, 0, 0); PG8_STAGE(PG8_SA(1, 1), a1 + hstepA, voffA);
;             PG8_WAIT_V(8); PG8_WAIT_L(0); PG8_BAR; PG8_MMA(0, 0, At, B0); PG8_MMA(0, 1, At, B1); PG8_BAR; PG8_SCHED;
;             PG8_LDA(At, 0, 1); PG8_STAGE(PG8_SB(0, 0), b2, voffB); PG8_STAGE(PG8_SB(0, 1), b2 + hstepB, voffB); PG8_STAGE(PG8_SA(0, 0), a2, voffA);
;             PG8_WAIT_V(8); PG8_WAIT_L(0); PG8_BAR; PG8_MMA(1, 0, At, B0); PG8_MMA(1, 1, At, B1); PG8_BAR; PG8_SCHED;
.LBB0_1186:
	s_cmp_gt_i32 s0, 0
	s_cselect_b64 s[24:25], -1, 0
	s_and_b64 s[24:25], s[22:23], s[24:25]
	s_lshl_b64 s[26:27], s[0:1], 9
	s_and_b64 s[24:25], s[24:25], exec
	s_cselect_b32 s54, s27, 0
	s_cselect_b32 s55, s26, 0
	s_ashr_i32 s19, s18, 31
	s_lshl_b64 s[24:25], s[18:19], 19
	s_add_u32 s19, s33, s24
	s_addc_u32 s21, s60, s25
	s_add_u32 s24, s19, s55
	s_addc_u32 s25, s21, s54
	s_and_b64 s[26:27], s[22:23], exec
	s_cselect_b32 s19, s25, s57
	s_cselect_b32 s31, s24, s56
	s_ashr_i32 s21, s20, 31
	s_lshl_b64 s[26:27], s[20:21], 19
	s_add_u32 s21, s2, s26
	s_addc_u32 s27, s3, s27
	s_add_u32 s26, s21, s55
	s_addc_u32 s27, s27, s54
	s_and_b64 s[54:55], s[22:23], exec
	s_cselect_b32 s21, s27, s35
	s_cselect_b32 s75, s26, s34
	s_cmp_gt_i32 s30, -1
	s_cselect_b64 s[54:55], -1, 0
	s_cmp_lt_i32 s30, 0
	s_cselect_b32 s76, 16, 4
	s_add_i32 s77, s76, -2
	s_add_u32 s56, s56, 0x40080
	s_addc_u32 s57, s57, 0
	s_add_u32 s78, s34, 0x100
	s_mov_b32 s58, 0
	s_addc_u32 s79, s35, 0
	ds_read_b128 v[18:21], v187
	ds_read_b128 v[26:29], v187 offset:2048
	ds_read_b128 v[22:25], v188
	ds_read_b128 v[30:33], v188 offset:2048
	ds_read_b128 v[2:5], v189
	ds_read_b128 v[10:13], v189 offset:2048
	ds_read_b128 v[6:9], v190
	ds_read_b128 v[14:17], v190 offset:2048
	s_add_i32 s80, s58, 2
	s_add_u32 s34, s56, 0xfffc0080
	s_addc_u32 s35, s57, -1
	s_cmp_eq_u32 s77, s58
	s_cselect_b32 s58, s31, s34
	s_cselect_b32 s59, s19, s35
	s_cselect_b32 s35, s21, s79
	s_cselect_b32 s34, s75, s78
	s_add_i32 m0, s29, 0xc000
	ds_read_b128 v[174:177], v191
	ds_read_b128 v[194:197], v191 offset:2048
	ds_read_b128 v[178:181], v192
	ds_read_b128 v[198:201], v192 offset:2048
	ds_read_b128 v[202:205], v191 offset:4096
	ds_read_b128 v[210:213], v191 offset:6144
	ds_read_b128 v[206:209], v192 offset:4096
	ds_read_b128 v[214:217], v192 offset:6144
	global_load_lds_dwordx4 v170, s[56:57]
	s_add_i32 m0, s29, 0xe000
	s_nop 0
	global_load_lds_dwordx4 v172, s[56:57]
	s_waitcnt vmcnt(8)
	s_waitcnt lgkmcnt(0)
	s_barrier
	s_setprio 1
	s_waitcnt lgkmcnt(0)
	v_mfma_scale_f32_16x16x128_f8f6f4 v[158:161], v[18:25], v[174:181], 0, v1, v182 op_sel_hi:[0,0,0]
	v_mfma_scale_f32_16x16x128_f8f6f4 v[154:157], v[26:33], v[174:181], 0, v1, v182 op_sel_hi:[0,0,0]
	v_mfma_scale_f32_16x16x128_f8f6f4 v[150:153], v[18:25], v[194:201], 0, v1, v182 op_sel_hi:[0,0,0]
	v_mfma_scale_f32_16x16x128_f8f6f4 v[138:141], v[26:33], v[194:201], 0, v1, v182 op_sel_hi:[0,0,0]
	v_mfma_scale_f32_16x16x128_f8f6f4 v[130:133], v[18:25], v[202:209], 0, v1, v182 op_sel_hi:[0,0,0]
	v_mfma_scale_f32_16x16x128_f8f6f4 v[122:125], v[26:33], v[202:209], 0, v1, v182 op_sel_hi:[0,0,0]
	v_mfma_scale_f32_16x16x128_f8f6f4 v[118:121], v[18:25], v[210:217], 0, v1, v182 op_sel_hi:[0,0,0]
	v_mfma_scale_f32_16x16x128_f8f6f4 v[106:109], v[26:33], v[210:217], 0, v1, v182 op_sel_hi:[0,0,0]
	s_setprio 0
	s_setprio 1
	v_mfma_scale_f32_16x16x128_f8f6f4 v[146:149], v[2:9], v[174:181], 0, v1, v182 op_sel_hi:[0,0,0]
	v_mfma_scale_f32_16x16x128_f8f6f4 v[142:145], v[10:17], v[174:181], 0, v1, v182 op_sel_hi:[0,0,0]
	v_mfma_scale_f32_16x16x128_f8f6f4 v[134:137], v[2:9], v[194:201], 0, v1, v182 op_sel_hi:[0,0,0]
	v_mfma_scale_f32_16x16x128_f8f6f4 v[126:129], v[10:17], v[194:201], 0, v1, v182 op_sel_hi:[0,0,0]
	v_mfma_scale_f32_16x16x128_f8f6f4 v[114:117], v[2:9], v[202:209], 0, v1, v182 op_sel_hi:[0,0,0]
	v_mfma_scale_f32_16x16x128_f8f6f4 v[110:113], v[10:17], v[202:209], 0, v1, v182 op_sel_hi:[0,0,0]
	v_mfma_scale_f32_16x16x128_f8f6f4 v[102:105], v[2:9], v[210:217], 0, v1, v182 op_sel_hi:[0,0,0]
	v_mfma_scale_f32_16x16x128_f8f6f4 v[98:101], v[10:17], v[210:217], 0, v1, v182 op_sel_hi:[0,0,0]
	s_setprio 0
	s_barrier
	s_add_i32 s81, s71, s61
	s_mov_b32 m0, s81
	ds_read_b128 v[194:197], v191 offset:16384
	ds_read_b128 v[202:205], v191 offset:18432
	ds_read_b128 v[198:201], v192 offset:16384
	ds_read_b128 v[206:209], v192 offset:18432
	ds_read_b128 v[210:213], v191 offset:20480
	ds_read_b128 v[218:221], v191 offset:22528
	ds_read_b128 v[214:217], v192 offset:20480
	ds_read_b128 v[222:225], v192 offset:22528
	global_load_lds_dwordx4 v164, s[34:35]
	s_add_i32 m0, s81, 0x2000
	s_add_u32 s82, s34, 0x40000
	s_addc_u32 s83, s35, 0
	s_add_i32 s81, s72, s61
	global_load_lds_dwordx4 v168, s[34:35]
	s_mov_b32 m0, s81
	s_nop 0
	global_load_lds_dwordx4 v164, s[82:83]
	s_add_i32 m0, s81, 0x2000
	s_nop 0
	global_load_lds_dwordx4 v168, s[82:83]
	s_mov_b32 m0, s29
	s_nop 0
	global_load_lds_dwordx4 v162, s[58:59]
	s_mov_b32 m0, s53
	s_nop 0
	global_load_lds_dwordx4 v166, s[58:59]
	s_waitcnt vmcnt(8)
	s_waitcnt lgkmcnt(0)
	s_barrier
	s_setprio 1
	s_waitcnt lgkmcnt(0)
	v_mfma_scale_f32_16x16x128_f8f6f4 v[94:97], v[18:25], v[194:201], 0, v1, v182 op_sel_hi:[0,0,0]
	v_mfma_scale_f32_16x16x128_f8f6f4 v[90:93], v[26:33], v[194:201], 0, v1, v182 op_sel_hi:[0,0,0]
	v_mfma_scale_f32_16x16x128_f8f6f4 v[82:85], v[18:25], v[202:209], 0, v1, v182 op_sel_hi:[0,0,0]
	v_mfma_scale_f32_16x16x128_f8f6f4 v[74:77], v[26:33], v[202:209], 0, v1, v182 op_sel_hi:[0,0,0]
	v_mfma_scale_f32_16x16x128_f8f6f4 v[66:69], v[18:25], v[210:217], 0, v1, v182 op_sel_hi:[0,0,0]
	v_mfma_scale_f32_16x16x128_f8f6f4 v[58:61], v[26:33], v[210:217], 0, v1, v182 op_sel_hi:[0,0,0]
	v_mfma_scale_f32_16x16x128_f8f6f4 v[50:53], v[18:25], v[218:225], 0, v1, v182 op_sel_hi:[0,0,0]
	v_mfma_scale_f32_16x16x128_f8f6f4 v[42:45], v[26:33], v[218:225], 0, v1, v182 op_sel_hi:[0,0,0]
	s_setprio 0
	s_setprio 1
	v_mfma_scale_f32_16x16x128_f8f6f4 v[86:89], v[2:9], v[194:201], 0, v1, v182 op_sel_hi:[0,0,0]
	v_mfma_scale_f32_16x16x128_f8f6f4 v[78:81], v[10:17], v[194:201], 0, v1, v182 op_sel_hi:[0,0,0]
	v_mfma_scale_f32_16x16x128_f8f6f4 v[70:73], v[2:9], v[202:209], 0, v1, v182 op_sel_hi:[0,0,0]
	v_mfma_scale_f32_16x16x128_f8f6f4 v[62:65], v[10:17], v[202:209], 0, v1, v182 op_sel_hi:[0,0,0]
	v_mfma_scale_f32_16x16x128_f8f6f4 v[54:57], v[2:9], v[210:217], 0, v1, v182 op_sel_hi:[0,0,0]
	v_mfma_scale_f32_16x16x128_f8f6f4 v[46:49], v[10:17], v[210:217], 0, v1, v182 op_sel_hi:[0,0,0]
	v_mfma_scale_f32_16x16x128_f8f6f4 v[38:41], v[2:9], v[218:225], 0, v1, v182 op_sel_hi:[0,0,0]
	v_mfma_scale_f32_16x16x128_f8f6f4 v[34:37], v[10:17], v[218:225], 0, v1, v182 op_sel_hi:[0,0,0]
	s_setprio 0
	s_barrier
	s_branch .Lmid_3

; #define PG8_STAGE(bufoff, gbase, voff) do { _Pragma("unroll") for (int _i = 0; _i < 2; ++_i) \
;         __builtin_amdgcn_global_load_lds((const unsigned*)((const char*)(gbase) + (voff)[_i]), (PG8_LAS unsigned*)(lds + (bufoff) + ldsw + _i * 8192), 16, 0, 0); } while (0)
; #define PG8_LDA(dst, b, h) do { _Pragma("unroll") for (int m = 0; m < 4; ++m) _Pragma("unroll") for (int k = 0; k < 2; ++k) dst[m][k] = *(const PG8_LAS bf16x8*)(lds + PG8_SA(b, h) + aoff + m * 2048 + k * 1024); } while (0)
; #define PG8_LDB(dst, b, h) do { _Pragma("unroll") for (int n = 0; n < 2; ++n) _Pragma("unroll") for (int k = 0; k < 2; ++k) dst[n][k] = *(const PG8_LAS bf16x8*)(lds + PG8_SB(b, h) + boff + n * 2048 + k * 1024); } while (0)
; #define PG8_BAR __builtin_amdgcn_s_barrier()
; template <class Epi, class Sched, bool ALIGN_EPI = false>
; __device__ __forceinline__ void gemm_phase8(PG8_LAS unsigned char* lds, const Gemm g, const Sched& S, const Epi& E) {
;     ...
;         for (int t = 0; t < nt; t += 2) {
;             const bool last = (t == nt - 2);
;             const char* a1 = cA + (size_t)(t + 1) * kstep;
;             const char* a2 = last ? nA : cA + (size_t)(t + 2) * kstep; const char* b2 = last ? nB : cB + (size_t)(t + 2) * kstep;
;             const char* a3 = a2 + kstep; const char* b3 = b2 + kstep;
;             if (last && has_next) S.a_ready(nxt);
;             PG8_LDB(B0, 0, 0); PG8_LDB(B1, 0, 1); PG8_SCHED; PG8_LDA(At, 0, 0); PG8_STAGE(PG8_SA(1, 1), a1 + hstepA, voffA);
;             PG8_WAIT_V(8); PG8_WAIT_L(0); PG8_BAR; PG8_MMA(0, 0, At, B0); PG8_MMA(0, 1, At, B1); PG8_BAR; PG8_SCHED;
;             PG8_LDA(At, 0, 1); PG8_STAGE(PG8_SB(0, 0), b2, voffB); PG8_STAGE(PG8_SB(0, 1), b2 + hstepB, voffB); PG8_STAGE(PG8_SA(0, 0), a2, voffA);
;             PG8_WAIT_V(8); PG8_WAIT_L(0); PG8_BAR; PG8_MMA(1, 0, At, B0); PG8_MMA(1, 1, At, B1); PG8_BAR; PG8_SCHED;
;             PG8_LDB(B0, 1, 0); PG8_LDB(B1, 1, 1); PG8_SCHED; PG8_LDA(At, 1, 0); PG8_STAGE(PG8_SA(0, 1), a2 + hstepA, voffA);
;             PG8_WAIT_V(8); PG8_WAIT_L(0); PG8_BAR; PG8_MMA(0, 0, At, B0); PG8_MMA(0, 1, At, B1); PG8_BAR; PG8_SCHED;
;             PG8_LDA(At, 1, 1); PG8_STAGE(PG8_SB(1, 0), b3, voffB); PG8_STAGE(PG8_SB(1, 1), b3 + hstepB, voffB); PG8_STAGE(PG8_SA(1, 0), a3, voffA);
;             PG8_WAIT_V(8); PG8_WAIT_L(0); PG8_BAR; PG8_MMA(1, 0, At, B0); PG8_MMA(1, 1, At, B1); PG8_BAR; PG8_SCHED;
;         }
.Lmid_3:
	s_add_i32 s81, 0, 0x18000
	s_add_i32 s82, 0, 0x1c000
	v_add_u32_e32 v6, s81, v184
	v_add_u32_e32 v14, s81, v185
	v_add_u32_e32 v22, s82, v184
	v_add_u32_e32 v30, s82, v185
	ds_read_b128 v[2:5], v6
	ds_read_b128 v[10:13], v6 offset:2048
	ds_read_b128 v[6:9], v14
	ds_read_b128 v[14:17], v14 offset:2048
	ds_read_b128 v[18:21], v22
	ds_read_b128 v[26:29], v22 offset:2048
	ds_read_b128 v[22:25], v30
	ds_read_b128 v[30:33], v30 offset:2048
	s_add_u32 s58, s58, 0x40000
	s_addc_u32 s59, s59, 0
	s_mov_b32 m0, s62
	ds_read_b128 v[194:197], v191 offset:32768
	ds_read_b128 v[202:205], v191 offset:34816
	ds_read_b128 v[198:201], v192 offset:32768
	ds_read_b128 v[206:209], v192 offset:34816
	ds_read_b128 v[210:213], v191 offset:36864
	ds_read_b128 v[218:221], v191 offset:38912
	ds_read_b128 v[214:217], v192 offset:36864
	ds_read_b128 v[222:225], v192 offset:38912
	global_load_lds_dwordx4 v162, s[58:59]
	s_mov_b32 m0, s63
	s_nop 0
	global_load_lds_dwordx4 v166, s[58:59]
	s_waitcnt vmcnt(8)
	s_waitcnt lgkmcnt(0)
	s_barrier
	s_setprio 1
	s_waitcnt lgkmcnt(0)
	v_mfma_scale_f32_16x16x128_f8f6f4 v[158:161], v[2:9], v[194:201], v[158:161], v1, v182 op_sel_hi:[0,0,0]
	v_mfma_scale_f32_16x16x128_f8f6f4 v[154:157], v[10:17], v[194:201], v[154:157], v1, v182 op_sel_hi:[0,0,0]
	v_mfma_scale_f32_16x16x128_f8f6f4 v[150:153], v[2:9], v[202:209], v[150:153], v1, v182 op_sel_hi:[0,0,0]
	v_mfma_scale_f32_16x16x128_f8f6f4 v[138:141], v[10:17], v[202:209], v[138:141], v1, v182 op_sel_hi:[0,0,0]
	v_mfma_scale_f32_16x16x128_f8f6f4 v[130:133], v[2:9], v[210:217], v[130:133], v1, v182 op_sel_hi:[0,0,0]
	v_mfma_scale_f32_16x16x128_f8f6f4 v[122:125], v[10:17], v[210:217], v[122:125], v1, v182 op_sel_hi:[0,0,0]
	v_mfma_scale_f32_16x16x128_f8f6f4 v[118:121], v[2:9], v[218:225], v[118:121], v1, v182 op_sel_hi:[0,0,0]
	v_mfma_scale_f32_16x16x128_f8f6f4 v[106:109], v[10:17], v[218:225], v[106:109], v1, v182 op_sel_hi:[0,0,0]
	s_setprio 0
	s_setprio 1
	v_mfma_scale_f32_16x16x128_f8f6f4 v[146:149], v[18:25], v[194:201], v[146:149], v1, v182 op_sel_hi:[0,0,0]
	v_mfma_scale_f32_16x16x128_f8f6f4 v[142:145], v[26:33], v[194:201], v[142:145], v1, v182 op_sel_hi:[0,0,0]
	v_mfma_scale_f32_16x16x128_f8f6f4 v[134:137], v[18:25], v[202:209], v[134:137], v1, v182 op_sel_hi:[0,0,0]
	v_mfma_scale_f32_16x16x128_f8f6f4 v[126:129], v[26:33], v[202:209], v[126:129], v1, v182 op_sel_hi:[0,0,0]
	v_mfma_scale_f32_16x16x128_f8f6f4 v[114:117], v[18:25], v[210:217], v[114:117], v1, v182 op_sel_hi:[0,0,0]
	v_mfma_scale_f32_16x16x128_f8f6f4 v[110:113], v[26:33], v[210:217], v[110:113], v1, v182 op_sel_hi:[0,0,0]
	v_mfma_scale_f32_16x16x128_f8f6f4 v[102:105], v[18:25], v[218:225], v[102:105], v1, v182 op_sel_hi:[0,0,0]
	v_mfma_scale_f32_16x16x128_f8f6f4 v[98:101], v[26:33], v[218:225], v[98:101], v1, v182 op_sel_hi:[0,0,0]
	s_setprio 0
	s_barrier
	s_add_i32 s101, s81, s61
	s_add_u32 s98, s34, s10
	s_addc_u32 s99, s35, s11
	s_mov_b32 m0, s101
	ds_read_b128 v[194:197], v191 offset:49152
	ds_read_b128 v[202:205], v191 offset:51200
	ds_read_b128 v[198:201], v192 offset:49152
	ds_read_b128 v[206:209], v192 offset:51200
	ds_read_b128 v[210:213], v191 offset:53248
	ds_read_b128 v[218:221], v191 offset:55296
	ds_read_b128 v[214:217], v192 offset:53248
	ds_read_b128 v[222:225], v192 offset:55296
	global_load_lds_dwordx4 v164, s[98:99]
	s_add_i32 m0, s101, 0x2000
	s_add_u32 s34, s34, 0x40080
	s_addc_u32 s35, s35, 0
	s_add_i32 s101, s82, s61
	global_load_lds_dwordx4 v168, s[98:99]
	s_add_u32 s98, s58, s10
	s_addc_u32 s99, s59, s11
	s_sub_u32 s98, s98, 0x40000
	s_subb_u32 s99, s99, 0
	s_mov_b32 m0, s101
	s_nop 0
	global_load_lds_dwordx4 v164, s[34:35]
	s_add_i32 m0, s101, 0x2000
	s_nop 0
	global_load_lds_dwordx4 v168, s[34:35]
	s_mov_b32 m0, s69
	s_nop 0
	global_load_lds_dwordx4 v162, s[98:99]
	s_mov_b32 m0, s70
	s_nop 0
	global_load_lds_dwordx4 v166, s[98:99]
	s_waitcnt vmcnt(8)
	s_waitcnt lgkmcnt(0)
	s_barrier
	s_setprio 1
	s_waitcnt lgkmcnt(0)
	v_mfma_scale_f32_16x16x128_f8f6f4 v[94:97], v[2:9], v[194:201], v[94:97], v1, v182 op_sel_hi:[0,0,0]
	v_mfma_scale_f32_16x16x128_f8f6f4 v[90:93], v[10:17], v[194:201], v[90:93], v1, v182 op_sel_hi:[0,0,0]
	v_mfma_scale_f32_16x16x128_f8f6f4 v[82:85], v[2:9], v[202:209], v[82:85], v1, v182 op_sel_hi:[0,0,0]
	v_mfma_scale_f32_16x16x128_f8f6f4 v[74:77], v[10:17], v[202:209], v[74:77], v1, v182 op_sel_hi:[0,0,0]
	v_mfma_scale_f32_16x16x128_f8f6f4 v[66:69], v[2:9], v[210:217], v[66:69], v1, v182 op_sel_hi:[0,0,0]
	v_mfma_scale_f32_16x16x128_f8f6f4 v[58:61], v[10:17], v[210:217], v[58:61], v1, v182 op_sel_hi:[0,0,0]
	v_mfma_scale_f32_16x16x128_f8f6f4 v[50:53], v[2:9], v[218:225], v[50:53], v1, v182 op_sel_hi:[0,0,0]
	v_mfma_scale_f32_16x16x128_f8f6f4 v[42:45], v[10:17], v[218:225], v[42:45], v1, v182 op_sel_hi:[0,0,0]
	s_setprio 0
	s_setprio 1
	v_mfma_scale_f32_16x16x128_f8f6f4 v[86:89], v[18:25], v[194:201], v[86:89], v1, v182 op_sel_hi:[0,0,0]
	v_mfma_scale_f32_16x16x128_f8f6f4 v[78:81], v[26:33], v[194:201], v[78:81], v1, v182 op_sel_hi:[0,0,0]
	v_mfma_scale_f32_16x16x128_f8f6f4 v[70:73], v[18:25], v[202:209], v[70:73], v1, v182 op_sel_hi:[0,0,0]
	v_mfma_scale_f32_16x16x128_f8f6f4 v[62:65], v[26:33], v[202:209], v[62:65], v1, v182 op_sel_hi:[0,0,0]
	v_mfma_scale_f32_16x16x128_f8f6f4 v[54:57], v[18:25], v[210:217], v[54:57], v1, v182 op_sel_hi:[0,0,0]
	v_mfma_scale_f32_16x16x128_f8f6f4 v[46:49], v[26:33], v[210:217], v[46:49], v1, v182 op_sel_hi:[0,0,0]
	v_mfma_scale_f32_16x16x128_f8f6f4 v[38:41], v[18:25], v[218:225], v[38:41], v1, v182 op_sel_hi:[0,0,0]
	v_mfma_scale_f32_16x16x128_f8f6f4 v[34:37], v[26:33], v[218:225], v[34:37], v1, v182 op_sel_hi:[0,0,0]
	s_setprio 0
	s_barrier
	s_add_u32 s56, s56, 0x100
	s_addc_u32 s57, s57, 0
	s_add_u32 s78, s78, 0x100
	s_addc_u32 s79, s79, 0
	s_cmp_ge_u32 s80, s76
	s_mov_b32 s58, s80
	s_cbranch_scc0 .LBB0_1187
	s_and_b64 vcc, exec, s[12:13]
	s_cbranch_vccz .LBB0_1190
	s_barrier

; #define PG8_STAGE(bufoff, gbase, voff) do { _Pragma("unroll") for (int _i = 0; _i < 2; ++_i) \
;         __builtin_amdgcn_global_load_lds((const unsigned*)((const char*)(gbase) + (voff)[_i]), (PG8_LAS unsigned*)(lds + (bufoff) + ldsw + _i * 8192), 16, 0, 0); } while (0)
; #define PG8_LDA(dst, b, h) do { _Pragma("unroll") for (int m = 0; m < 4; ++m) _Pragma("unroll") for (int k = 0; k < 2; ++k) dst[m][k] = *(const PG8_LAS bf16x8*)(lds + PG8_SA(b, h) + aoff + m * 2048 + k * 1024); } while (0)
; #define PG8_LDB(dst, b, h) do { _Pragma("unroll") for (int n = 0; n < 2; ++n) _Pragma("unroll") for (int k = 0; k < 2; ++k) dst[n][k] = *(const PG8_LAS bf16x8*)(lds + PG8_SB(b, h) + boff + n * 2048 + k * 1024); } while (0)
; #define PG8_WAIT_V(n) asm volatile("s_waitcnt vmcnt(" #n ")" ::: "memory")
; #define PG8_WAIT_L(n) asm volatile("s_waitcnt lgkmcnt(" #n ")" ::: "memory")
; template <class Epi, class Sched, bool ALIGN_EPI = false>
; __device__ __forceinline__ void gemm_phase8(PG8_LAS unsigned char* lds, const Gemm g, const Sched& S, const Epi& E) {
;     ...
;         const bool has_next = S.next(ui + 1, nxt);
;         const size_t nko = (has_next && nxt.kp > 0) ? (size_t)nxt.kp * g.kpiece : 0;
;         const char* nA = has_next ? (const char*)g.A + (size_t)nxt.pm * tstepA + (size_t)nxt.pn * astep + nko : cA; const char* nB = has_next ? (const char*)g.Bt + (size_t)nxt.pn * tstepB + nko : cB;
;         const int nt = (cur.kp < 0 ? g.K : g.kpiece) / 128;
;         for (int t = 0; t < nt; t += 2) {
;             const bool last = (t == nt - 2);
;             const char* a1 = cA + (size_t)(t + 1) * kstep;
;             const char* a2 = last ? nA : cA + (size_t)(t + 2) * kstep; const char* b2 = last ? nB : cB + (size_t)(t + 2) * kstep;
;             const char* a3 = a2 + kstep; const char* b3 = b2 + kstep;
;             if (last && has_next) S.a_ready(nxt);
;             PG8_LDB(B0, 0, 0); PG8_LDB(B1, 0, 1); PG8_SCHED; PG8_LDA(At, 0, 0); PG8_STAGE(PG8_SA(1, 1), a1 + hstepA, voffA);
;             PG8_WAIT_V(8); PG8_WAIT_L(0); PG8_BAR; PG8_MMA(0, 0, At, B0); PG8_MMA(0, 1, At, B1); PG8_BAR; PG8_SCHED;
;             PG8_LDA(At, 0, 1); PG8_STAGE(PG8_SB(0, 0), b2, voffB); PG8_STAGE(PG8_SB(0, 1), b2 + hstepB, voffB); PG8_STAGE(PG8_SA(0, 0), a2, voffA);
;             PG8_WAIT_V(8); PG8_WAIT_L(0); PG8_BAR; PG8_MMA(1, 0, At, B0); PG8_MMA(1, 1, At, B1); PG8_BAR; PG8_SCHED;
.LBB0_1421:
	s_ashr_i32 s13, s12, 31
	s_lshl_b64 s[14:15], s[12:13], 19
	s_add_u32 s14, s26, s14
	s_addc_u32 s15, s27, s15
	s_and_b64 s[16:17], s[2:3], exec
	s_cselect_b32 s13, s15, s21
	s_cselect_b32 s45, s14, s20
	s_ashr_i32 s11, s10, 31
	s_lshl_b64 s[16:17], s[10:11], 19
	s_add_u32 s16, s28, s16
	s_addc_u32 s17, s29, s17
	s_and_b64 s[24:25], s[2:3], exec
	s_cselect_b32 s11, s17, s23
	s_cselect_b32 s52, s16, s22
	s_add_u32 s20, s20, 0x40080
	s_addc_u32 s21, s21, 0
	s_add_u32 s53, s22, 0x100
	s_addc_u32 s54, s23, 0
	s_mov_b32 s55, -2
	ds_read_b128 v[18:21], v191
	ds_read_b128 v[26:29], v191 offset:2048
	ds_read_b128 v[22:25], v192
	ds_read_b128 v[30:33], v192 offset:2048
	ds_read_b128 v[2:5], v193
	ds_read_b128 v[10:13], v193 offset:2048
	ds_read_b128 v[6:9], v194
	ds_read_b128 v[14:17], v194 offset:2048
	s_add_u32 s22, s20, 0xfffc0080
	s_addc_u32 s23, s21, -1
	s_cmp_eq_u32 s55, 12
	s_cselect_b32 s25, s13, s23
	s_cselect_b32 s24, s45, s22
	s_cselect_b32 s23, s11, s54
	s_cselect_b32 s22, s52, s53
	s_add_i32 m0, s19, 0xc000
	ds_read_b128 v[178:181], v195
	ds_read_b128 v[198:201], v195 offset:2048
	ds_read_b128 v[182:185], v196
	ds_read_b128 v[202:205], v196 offset:2048
	ds_read_b128 v[206:209], v195 offset:4096
	ds_read_b128 v[214:217], v195 offset:6144
	ds_read_b128 v[210:213], v196 offset:4096
	ds_read_b128 v[218:221], v196 offset:6144
	global_load_lds_dwordx4 v170, s[20:21]
	s_add_i32 m0, s19, 0xe000
	s_nop 0
	global_load_lds_dwordx4 v172, s[20:21]
	s_waitcnt vmcnt(8)
	s_waitcnt lgkmcnt(0)
	s_barrier
	s_setprio 1
	s_waitcnt lgkmcnt(0)
	v_mfma_scale_f32_16x16x128_f8f6f4 v[158:161], v[18:25], v[178:185], 0, v1, v186 op_sel_hi:[0,0,0]
	v_mfma_scale_f32_16x16x128_f8f6f4 v[150:153], v[26:33], v[178:185], 0, v1, v186 op_sel_hi:[0,0,0]
	v_mfma_scale_f32_16x16x128_f8f6f4 v[142:145], v[18:25], v[198:205], 0, v1, v186 op_sel_hi:[0,0,0]
	v_mfma_scale_f32_16x16x128_f8f6f4 v[134:137], v[26:33], v[198:205], 0, v1, v186 op_sel_hi:[0,0,0]
	v_mfma_scale_f32_16x16x128_f8f6f4 v[126:129], v[18:25], v[206:213], 0, v1, v186 op_sel_hi:[0,0,0]
	v_mfma_scale_f32_16x16x128_f8f6f4 v[118:121], v[26:33], v[206:213], 0, v1, v186 op_sel_hi:[0,0,0]
	v_mfma_scale_f32_16x16x128_f8f6f4 v[110:113], v[18:25], v[214:221], 0, v1, v186 op_sel_hi:[0,0,0]
	v_mfma_scale_f32_16x16x128_f8f6f4 v[102:105], v[26:33], v[214:221], 0, v1, v186 op_sel_hi:[0,0,0]
	s_setprio 0
	s_setprio 1
	v_mfma_scale_f32_16x16x128_f8f6f4 v[154:157], v[2:9], v[178:185], 0, v1, v186 op_sel_hi:[0,0,0]
	v_mfma_scale_f32_16x16x128_f8f6f4 v[146:149], v[10:17], v[178:185], 0, v1, v186 op_sel_hi:[0,0,0]
	v_mfma_scale_f32_16x16x128_f8f6f4 v[138:141], v[2:9], v[198:205], 0, v1, v186 op_sel_hi:[0,0,0]
	v_mfma_scale_f32_16x16x128_f8f6f4 v[130:133], v[10:17], v[198:205], 0, v1, v186 op_sel_hi:[0,0,0]
	v_mfma_scale_f32_16x16x128_f8f6f4 v[122:125], v[2:9], v[206:213], 0, v1, v186 op_sel_hi:[0,0,0]
	v_mfma_scale_f32_16x16x128_f8f6f4 v[114:117], v[10:17], v[206:213], 0, v1, v186 op_sel_hi:[0,0,0]
	v_mfma_scale_f32_16x16x128_f8f6f4 v[106:109], v[2:9], v[214:221], 0, v1, v186 op_sel_hi:[0,0,0]
	v_mfma_scale_f32_16x16x128_f8f6f4 v[98:101], v[10:17], v[214:221], 0, v1, v186 op_sel_hi:[0,0,0]
	s_setprio 0
	s_barrier
	s_add_i32 s56, s41, s30
	s_mov_b32 m0, s56
	ds_read_b128 v[198:201], v195 offset:16384
	ds_read_b128 v[206:209], v195 offset:18432
	ds_read_b128 v[202:205], v196 offset:16384
	ds_read_b128 v[210:213], v196 offset:18432
	ds_read_b128 v[214:217], v195 offset:20480
	ds_read_b128 v[222:225], v195 offset:22528
	ds_read_b128 v[218:221], v196 offset:20480
	ds_read_b128 v[226:229], v196 offset:22528
	global_load_lds_dwordx4 v164, s[22:23]
	s_add_i32 m0, s56, 0x2000
	s_add_u32 s56, s22, 0x40000
	s_addc_u32 s57, s23, 0
	s_add_i32 s58, s42, s30
	global_load_lds_dwordx4 v168, s[22:23]
	s_mov_b32 m0, s58
	s_nop 0
	global_load_lds_dwordx4 v164, s[56:57]
	s_add_i32 m0, s58, 0x2000
	s_nop 0
	global_load_lds_dwordx4 v168, s[56:57]
	s_mov_b32 m0, s19
	s_nop 0
	global_load_lds_dwordx4 v162, s[24:25]
	s_mov_b32 m0, s34
	s_nop 0
	global_load_lds_dwordx4 v166, s[24:25]
	s_waitcnt vmcnt(8)
	s_waitcnt lgkmcnt(0)
	s_barrier
	s_setprio 1
	s_waitcnt lgkmcnt(0)
	v_mfma_scale_f32_16x16x128_f8f6f4 v[94:97], v[18:25], v[198:205], 0, v1, v186 op_sel_hi:[0,0,0]
	v_mfma_scale_f32_16x16x128_f8f6f4 v[86:89], v[26:33], v[198:205], 0, v1, v186 op_sel_hi:[0,0,0]
	v_mfma_scale_f32_16x16x128_f8f6f4 v[78:81], v[18:25], v[206:213], 0, v1, v186 op_sel_hi:[0,0,0]
	v_mfma_scale_f32_16x16x128_f8f6f4 v[70:73], v[26:33], v[206:213], 0, v1, v186 op_sel_hi:[0,0,0]
	v_mfma_scale_f32_16x16x128_f8f6f4 v[62:65], v[18:25], v[214:221], 0, v1, v186 op_sel_hi:[0,0,0]
	v_mfma_scale_f32_16x16x128_f8f6f4 v[54:57], v[26:33], v[214:221], 0, v1, v186 op_sel_hi:[0,0,0]
	v_mfma_scale_f32_16x16x128_f8f6f4 v[46:49], v[18:25], v[222:229], 0, v1, v186 op_sel_hi:[0,0,0]
	v_mfma_scale_f32_16x16x128_f8f6f4 v[38:41], v[26:33], v[222:229], 0, v1, v186 op_sel_hi:[0,0,0]
	s_setprio 0
	s_setprio 1
	v_mfma_scale_f32_16x16x128_f8f6f4 v[90:93], v[2:9], v[198:205], 0, v1, v186 op_sel_hi:[0,0,0]
	v_mfma_scale_f32_16x16x128_f8f6f4 v[82:85], v[10:17], v[198:205], 0, v1, v186 op_sel_hi:[0,0,0]
	v_mfma_scale_f32_16x16x128_f8f6f4 v[74:77], v[2:9], v[206:213], 0, v1, v186 op_sel_hi:[0,0,0]
	v_mfma_scale_f32_16x16x128_f8f6f4 v[66:69], v[10:17], v[206:213], 0, v1, v186 op_sel_hi:[0,0,0]
	v_mfma_scale_f32_16x16x128_f8f6f4 v[58:61], v[2:9], v[214:221], 0, v1, v186 op_sel_hi:[0,0,0]
	v_mfma_scale_f32_16x16x128_f8f6f4 v[50:53], v[10:17], v[214:221], 0, v1, v186 op_sel_hi:[0,0,0]
	v_mfma_scale_f32_16x16x128_f8f6f4 v[42:45], v[2:9], v[222:229], 0, v1, v186 op_sel_hi:[0,0,0]
	v_mfma_scale_f32_16x16x128_f8f6f4 v[34:37], v[10:17], v[222:229], 0, v1, v186 op_sel_hi:[0,0,0]
	s_setprio 0
	s_barrier
	s_branch .Lmid_4

; #define PG8_STAGE(bufoff, gbase, voff) do { _Pragma("unroll") for (int _i = 0; _i < 2; ++_i) \
;         __builtin_amdgcn_global_load_lds((const unsigned*)((const char*)(gbase) + (voff)[_i]), (PG8_LAS unsigned*)(lds + (bufoff) + ldsw + _i * 8192), 16, 0, 0); } while (0)
; #define PG8_LDA(dst, b, h) do { _Pragma("unroll") for (int m = 0; m < 4; ++m) _Pragma("unroll") for (int k = 0; k < 2; ++k) dst[m][k] = *(const PG8_LAS bf16x8*)(lds + PG8_SA(b, h) + aoff + m * 2048 + k * 1024); } while (0)
; #define PG8_LDB(dst, b, h) do { _Pragma("unroll") for (int n = 0; n < 2; ++n) _Pragma("unroll") for (int k = 0; k < 2; ++k) dst[n][k] = *(const PG8_LAS bf16x8*)(lds + PG8_SB(b, h) + boff + n * 2048 + k * 1024); } while (0)
; #define PG8_BAR __builtin_amdgcn_s_barrier()
; template <class Epi, class Sched, bool ALIGN_EPI = false>
; __device__ __forceinline__ void gemm_phase8(PG8_LAS unsigned char* lds, const Gemm g, const Sched& S, const Epi& E) {
;     ...
;         for (int t = 0; t < nt; t += 2) {
;             const bool last = (t == nt - 2);
;             const char* a1 = cA + (size_t)(t + 1) * kstep;
;             const char* a2 = last ? nA : cA + (size_t)(t + 2) * kstep; const char* b2 = last ? nB : cB + (size_t)(t + 2) * kstep;
;             const char* a3 = a2 + kstep; const char* b3 = b2 + kstep;
;             if (last && has_next) S.a_ready(nxt);
;             PG8_LDB(B0, 0, 0); PG8_LDB(B1, 0, 1); PG8_SCHED; PG8_LDA(At, 0, 0); PG8_STAGE(PG8_SA(1, 1), a1 + hstepA, voffA);
;             PG8_WAIT_V(8); PG8_WAIT_L(0); PG8_BAR; PG8_MMA(0, 0, At, B0); PG8_MMA(0, 1, At, B1); PG8_BAR; PG8_SCHED;
;             PG8_LDA(At, 0, 1); PG8_STAGE(PG8_SB(0, 0), b2, voffB); PG8_STAGE(PG8_SB(0, 1), b2 + hstepB, voffB); PG8_STAGE(PG8_SA(0, 0), a2, voffA);
;             PG8_WAIT_V(8); PG8_WAIT_L(0); PG8_BAR; PG8_MMA(1, 0, At, B0); PG8_MMA(1, 1, At, B1); PG8_BAR; PG8_SCHED;
;             PG8_LDB(B0, 1, 0); PG8_LDB(B1, 1, 1); PG8_SCHED; PG8_LDA(At, 1, 0); PG8_STAGE(PG8_SA(0, 1), a2 + hstepA, voffA);
;             PG8_WAIT_V(8); PG8_WAIT_L(0); PG8_BAR; PG8_MMA(0, 0, At, B0); PG8_MMA(0, 1, At, B1); PG8_BAR; PG8_SCHED;
;             PG8_LDA(At, 1, 1); PG8_STAGE(PG8_SB(1, 0), b3, voffB); PG8_STAGE(PG8_SB(1, 1), b3 + hstepB, voffB); PG8_STAGE(PG8_SA(1, 0), a3, voffA);
;             PG8_WAIT_V(8); PG8_WAIT_L(0); PG8_BAR; PG8_MMA(1, 0, At, B0); PG8_MMA(1, 1, At, B1); PG8_BAR; PG8_SCHED;
;         }
.Lmid_4:
	s_add_i32 s56, 0, 0x18000
	s_add_i32 s57, 0, 0x1c000
	v_add_u32_e32 v6, s56, v187
	v_add_u32_e32 v14, s56, v188
	v_add_u32_e32 v22, s57, v187
	v_add_u32_e32 v30, s57, v188
	ds_read_b128 v[2:5], v6
	ds_read_b128 v[10:13], v6 offset:2048
	ds_read_b128 v[6:9], v14
	ds_read_b128 v[14:17], v14 offset:2048
	ds_read_b128 v[18:21], v22
	ds_read_b128 v[26:29], v22 offset:2048
	ds_read_b128 v[22:25], v30
	ds_read_b128 v[30:33], v30 offset:2048
	s_add_u32 s24, s24, 0x40000
	s_addc_u32 s25, s25, 0
	s_mov_b32 m0, s35
	ds_read_b128 v[198:201], v195 offset:32768
	ds_read_b128 v[206:209], v195 offset:34816
	ds_read_b128 v[202:205], v196 offset:32768
	ds_read_b128 v[210:213], v196 offset:34816
	ds_read_b128 v[214:217], v195 offset:36864
	ds_read_b128 v[222:225], v195 offset:38912
	ds_read_b128 v[218:221], v196 offset:36864
	ds_read_b128 v[226:229], v196 offset:38912
	global_load_lds_dwordx4 v162, s[24:25]
	s_mov_b32 m0, s36
	s_nop 0
	global_load_lds_dwordx4 v166, s[24:25]
	s_waitcnt vmcnt(8)
	s_waitcnt lgkmcnt(0)
	s_barrier
	s_setprio 1
	s_waitcnt lgkmcnt(0)
	v_mfma_scale_f32_16x16x128_f8f6f4 v[158:161], v[2:9], v[198:205], v[158:161], v1, v186 op_sel_hi:[0,0,0]
	v_mfma_scale_f32_16x16x128_f8f6f4 v[150:153], v[10:17], v[198:205], v[150:153], v1, v186 op_sel_hi:[0,0,0]
	v_mfma_scale_f32_16x16x128_f8f6f4 v[142:145], v[2:9], v[206:213], v[142:145], v1, v186 op_sel_hi:[0,0,0]
	v_mfma_scale_f32_16x16x128_f8f6f4 v[134:137], v[10:17], v[206:213], v[134:137], v1, v186 op_sel_hi:[0,0,0]
	v_mfma_scale_f32_16x16x128_f8f6f4 v[126:129], v[2:9], v[214:221], v[126:129], v1, v186 op_sel_hi:[0,0,0]
	v_mfma_scale_f32_16x16x128_f8f6f4 v[118:121], v[10:17], v[214:221], v[118:121], v1, v186 op_sel_hi:[0,0,0]
	v_mfma_scale_f32_16x16x128_f8f6f4 v[110:113], v[2:9], v[222:229], v[110:113], v1, v186 op_sel_hi:[0,0,0]
	v_mfma_scale_f32_16x16x128_f8f6f4 v[102:105], v[10:17], v[222:229], v[102:105], v1, v186 op_sel_hi:[0,0,0]
	s_setprio 0
	s_setprio 1
	v_mfma_scale_f32_16x16x128_f8f6f4 v[154:157], v[18:25], v[198:205], v[154:157], v1, v186 op_sel_hi:[0,0,0]
	v_mfma_scale_f32_16x16x128_f8f6f4 v[146:149], v[26:33], v[198:205], v[146:149], v1, v186 op_sel_hi:[0,0,0]
	v_mfma_scale_f32_16x16x128_f8f6f4 v[138:141], v[18:25], v[206:213], v[138:141], v1, v186 op_sel_hi:[0,0,0]
	v_mfma_scale_f32_16x16x128_f8f6f4 v[130:133], v[26:33], v[206:213], v[130:133], v1, v186 op_sel_hi:[0,0,0]
	v_mfma_scale_f32_16x16x128_f8f6f4 v[122:125], v[18:25], v[214:221], v[122:125], v1, v186 op_sel_hi:[0,0,0]
	v_mfma_scale_f32_16x16x128_f8f6f4 v[114:117], v[26:33], v[214:221], v[114:117], v1, v186 op_sel_hi:[0,0,0]
	v_mfma_scale_f32_16x16x128_f8f6f4 v[106:109], v[18:25], v[222:229], v[106:109], v1, v186 op_sel_hi:[0,0,0]
	v_mfma_scale_f32_16x16x128_f8f6f4 v[98:101], v[26:33], v[222:229], v[98:101], v1, v186 op_sel_hi:[0,0,0]
	s_setprio 0
	s_barrier
	s_add_i32 s101, s56, s30
	s_add_u32 s98, s22, s6
	s_addc_u32 s99, s23, s7
	s_mov_b32 m0, s101
	ds_read_b128 v[198:201], v195 offset:49152
	ds_read_b128 v[206:209], v195 offset:51200
	ds_read_b128 v[202:205], v196 offset:49152
	ds_read_b128 v[210:213], v196 offset:51200
	ds_read_b128 v[214:217], v195 offset:53248
	ds_read_b128 v[222:225], v195 offset:55296
	ds_read_b128 v[218:221], v196 offset:53248
	ds_read_b128 v[226:229], v196 offset:55296
	global_load_lds_dwordx4 v164, s[98:99]
	s_add_i32 m0, s101, 0x2000
	s_add_u32 s22, s22, 0x40080
	s_addc_u32 s23, s23, 0
	s_add_i32 s101, s57, s30
	global_load_lds_dwordx4 v168, s[98:99]
	s_add_u32 s98, s24, s6
	s_addc_u32 s99, s25, s7
	s_sub_u32 s98, s98, 0x40000
	s_subb_u32 s99, s99, 0
	s_mov_b32 m0, s101
	s_nop 0
	global_load_lds_dwordx4 v164, s[22:23]
	s_add_i32 m0, s101, 0x2000
	s_nop 0
	global_load_lds_dwordx4 v168, s[22:23]
	s_mov_b32 m0, s39
	s_nop 0
	global_load_lds_dwordx4 v162, s[98:99]
	s_mov_b32 m0, s40
	s_nop 0
	global_load_lds_dwordx4 v166, s[98:99]
	s_waitcnt vmcnt(8)
	s_waitcnt lgkmcnt(0)
	s_barrier
	s_setprio 1
	s_waitcnt lgkmcnt(0)
	v_mfma_scale_f32_16x16x128_f8f6f4 v[94:97], v[2:9], v[198:205], v[94:97], v1, v186 op_sel_hi:[0,0,0]
	v_mfma_scale_f32_16x16x128_f8f6f4 v[86:89], v[10:17], v[198:205], v[86:89], v1, v186 op_sel_hi:[0,0,0]
	v_mfma_scale_f32_16x16x128_f8f6f4 v[78:81], v[2:9], v[206:213], v[78:81], v1, v186 op_sel_hi:[0,0,0]
	v_mfma_scale_f32_16x16x128_f8f6f4 v[70:73], v[10:17], v[206:213], v[70:73], v1, v186 op_sel_hi:[0,0,0]
	v_mfma_scale_f32_16x16x128_f8f6f4 v[62:65], v[2:9], v[214:221], v[62:65], v1, v186 op_sel_hi:[0,0,0]
	v_mfma_scale_f32_16x16x128_f8f6f4 v[54:57], v[10:17], v[214:221], v[54:57], v1, v186 op_sel_hi:[0,0,0]
	v_mfma_scale_f32_16x16x128_f8f6f4 v[46:49], v[2:9], v[222:229], v[46:49], v1, v186 op_sel_hi:[0,0,0]
	v_mfma_scale_f32_16x16x128_f8f6f4 v[38:41], v[10:17], v[222:229], v[38:41], v1, v186 op_sel_hi:[0,0,0]
	s_setprio 0
	s_setprio 1
	v_mfma_scale_f32_16x16x128_f8f6f4 v[90:93], v[18:25], v[198:205], v[90:93], v1, v186 op_sel_hi:[0,0,0]
	v_mfma_scale_f32_16x16x128_f8f6f4 v[82:85], v[26:33], v[198:205], v[82:85], v1, v186 op_sel_hi:[0,0,0]
	v_mfma_scale_f32_16x16x128_f8f6f4 v[74:77], v[18:25], v[206:213], v[74:77], v1, v186 op_sel_hi:[0,0,0]
	v_mfma_scale_f32_16x16x128_f8f6f4 v[66:69], v[26:33], v[206:213], v[66:69], v1, v186 op_sel_hi:[0,0,0]
	v_mfma_scale_f32_16x16x128_f8f6f4 v[58:61], v[18:25], v[214:221], v[58:61], v1, v186 op_sel_hi:[0,0,0]
	v_mfma_scale_f32_16x16x128_f8f6f4 v[50:53], v[26:33], v[214:221], v[50:53], v1, v186 op_sel_hi:[0,0,0]
	v_mfma_scale_f32_16x16x128_f8f6f4 v[42:45], v[18:25], v[222:229], v[42:45], v1, v186 op_sel_hi:[0,0,0]
	v_mfma_scale_f32_16x16x128_f8f6f4 v[34:37], v[26:33], v[222:229], v[34:37], v1, v186 op_sel_hi:[0,0,0]
	s_setprio 0
	s_barrier
	s_add_i32 s55, s55, 2
	s_add_u32 s20, s20, 0x100
	s_addc_u32 s21, s21, 0
	s_add_u32 s53, s53, 0x100
	s_addc_u32 s54, s54, 0
	s_cmp_gt_u32 s55, 13
	s_cbranch_scc0 .LBB0_1422
	s_and_b64 vcc, exec, s[8:9]
	s_cbranch_vccz .LBB0_1425
	s_barrier

; #define PG8_STAGE(bufoff, gbase, voff) do { _Pragma("unroll") for (int _i = 0; _i < 2; ++_i) \
;         __builtin_amdgcn_global_load_lds((const unsigned*)((const char*)(gbase) + (voff)[_i]), (PG8_LAS unsigned*)(lds + (bufoff) + ldsw + _i * 8192), 16, 0, 0); } while (0)
; #define PG8_LDA(dst, b, h) do { _Pragma("unroll") for (int m = 0; m < 4; ++m) _Pragma("unroll") for (int k = 0; k < 2; ++k) dst[m][k] = *(const PG8_LAS bf16x8*)(lds + PG8_SA(b, h) + aoff + m * 2048 + k * 1024); } while (0)
; #define PG8_LDB(dst, b, h) do { _Pragma("unroll") for (int n = 0; n < 2; ++n) _Pragma("unroll") for (int k = 0; k < 2; ++k) dst[n][k] = *(const PG8_LAS bf16x8*)(lds + PG8_SB(b, h) + boff + n * 2048 + k * 1024); } while (0)
; #define PG8_WAIT_V(n) asm volatile("s_waitcnt vmcnt(" #n ")" ::: "memory")
; #define PG8_WAIT_L(n) asm volatile("s_waitcnt lgkmcnt(" #n ")" ::: "memory")
; template <class Epi, class Sched, bool ALIGN_EPI = false>
; __device__ __forceinline__ void gemm_phase8(PG8_LAS unsigned char* lds, const Gemm g, const Sched& S, const Epi& E) {
;     ...
;         const bool has_next = S.next(ui + 1, nxt);
;         const size_t nko = (has_next && nxt.kp > 0) ? (size_t)nxt.kp * g.kpiece : 0;
;         const char* nA = has_next ? (const char*)g.A + (size_t)nxt.pm * tstepA + (size_t)nxt.pn * astep + nko : cA; const char* nB = has_next ? (const char*)g.Bt + (size_t)nxt.pn * tstepB + nko : cB;
;         const int nt = (cur.kp < 0 ? g.K : g.kpiece) / 128;
;         for (int t = 0; t < nt; t += 2) {
;             const bool last = (t == nt - 2);
;             const char* a1 = cA + (size_t)(t + 1) * kstep;
;             const char* a2 = last ? nA : cA + (size_t)(t + 2) * kstep; const char* b2 = last ? nB : cB + (size_t)(t + 2) * kstep;
;             const char* a3 = a2 + kstep; const char* b3 = b2 + kstep;
;             if (last && has_next) S.a_ready(nxt);
;             PG8_LDB(B0, 0, 0); PG8_LDB(B1, 0, 1); PG8_SCHED; PG8_LDA(At, 0, 0); PG8_STAGE(PG8_SA(1, 1), a1 + hstepA, voffA);
;             PG8_WAIT_V(8); PG8_WAIT_L(0); PG8_BAR; PG8_MMA(0, 0, At, B0); PG8_MMA(0, 1, At, B1); PG8_BAR; PG8_SCHED;
;             PG8_LDA(At, 0, 1); PG8_STAGE(PG8_SB(0, 0), b2, voffB); PG8_STAGE(PG8_SB(0, 1), b2 + hstepB, voffB); PG8_STAGE(PG8_SA(0, 0), a2, voffA);
;             PG8_WAIT_V(8); PG8_WAIT_L(0); PG8_BAR; PG8_MMA(1, 0, At, B0); PG8_MMA(1, 1, At, B1); PG8_BAR; PG8_SCHED;
.LBB0_1510:
	s_cmp_gt_i32 s30, -1
	s_cselect_b64 s[36:37], -1, 0
	s_cmp_lt_i32 s30, 0
	s_cselect_b32 s31, 44, 4
	s_add_i32 s79, s31, -2
	s_add_u32 s38, s38, 0xb0080
	s_addc_u32 s39, s39, 0
	s_add_u32 s80, s34, 0x100
	s_mov_b32 s40, 0
	s_addc_u32 s81, s35, 0
	ds_read_b128 v[18:21], v187
	ds_read_b128 v[26:29], v187 offset:2048
	ds_read_b128 v[22:25], v188
	ds_read_b128 v[30:33], v188 offset:2048
	ds_read_b128 v[2:5], v189
	ds_read_b128 v[10:13], v189 offset:2048
	ds_read_b128 v[6:9], v190
	ds_read_b128 v[14:17], v190 offset:2048
	s_add_i32 s82, s40, 2
	s_add_u32 s34, s38, 0xfff50080
	s_addc_u32 s35, s39, -1
	s_cmp_eq_u32 s79, s40
	s_cselect_b32 s40, s26, s34
	s_cselect_b32 s41, s27, s35
	s_cselect_b32 s35, s29, s81
	s_cselect_b32 s34, s28, s80
	s_add_i32 m0, s52, 0xc000
	ds_read_b128 v[174:177], v191
	ds_read_b128 v[194:197], v191 offset:2048
	ds_read_b128 v[178:181], v192
	ds_read_b128 v[198:201], v192 offset:2048
	ds_read_b128 v[202:205], v191 offset:4096
	ds_read_b128 v[210:213], v191 offset:6144
	ds_read_b128 v[206:209], v192 offset:4096
	ds_read_b128 v[214:217], v192 offset:6144
	global_load_lds_dwordx4 v170, s[38:39]
	s_add_i32 m0, s52, 0xe000
	s_nop 0
	global_load_lds_dwordx4 v172, s[38:39]
	s_waitcnt vmcnt(8)
	s_waitcnt lgkmcnt(0)
	s_barrier
	s_setprio 1
	s_waitcnt lgkmcnt(0)
	v_mfma_scale_f32_16x16x128_f8f6f4 v[158:161], v[18:25], v[174:181], 0, v1, v182 op_sel_hi:[0,0,0]
	v_mfma_scale_f32_16x16x128_f8f6f4 v[154:157], v[26:33], v[174:181], 0, v1, v182 op_sel_hi:[0,0,0]
	v_mfma_scale_f32_16x16x128_f8f6f4 v[150:153], v[18:25], v[194:201], 0, v1, v182 op_sel_hi:[0,0,0]
	v_mfma_scale_f32_16x16x128_f8f6f4 v[138:141], v[26:33], v[194:201], 0, v1, v182 op_sel_hi:[0,0,0]
	v_mfma_scale_f32_16x16x128_f8f6f4 v[130:133], v[18:25], v[202:209], 0, v1, v182 op_sel_hi:[0,0,0]
	v_mfma_scale_f32_16x16x128_f8f6f4 v[122:125], v[26:33], v[202:209], 0, v1, v182 op_sel_hi:[0,0,0]
	v_mfma_scale_f32_16x16x128_f8f6f4 v[118:121], v[18:25], v[210:217], 0, v1, v182 op_sel_hi:[0,0,0]
	v_mfma_scale_f32_16x16x128_f8f6f4 v[106:109], v[26:33], v[210:217], 0, v1, v182 op_sel_hi:[0,0,0]
	s_setprio 0
	s_setprio 1
	v_mfma_scale_f32_16x16x128_f8f6f4 v[146:149], v[2:9], v[174:181], 0, v1, v182 op_sel_hi:[0,0,0]
	v_mfma_scale_f32_16x16x128_f8f6f4 v[142:145], v[10:17], v[174:181], 0, v1, v182 op_sel_hi:[0,0,0]
	v_mfma_scale_f32_16x16x128_f8f6f4 v[134:137], v[2:9], v[194:201], 0, v1, v182 op_sel_hi:[0,0,0]
	v_mfma_scale_f32_16x16x128_f8f6f4 v[126:129], v[10:17], v[194:201], 0, v1, v182 op_sel_hi:[0,0,0]
	v_mfma_scale_f32_16x16x128_f8f6f4 v[114:117], v[2:9], v[202:209], 0, v1, v182 op_sel_hi:[0,0,0]
	v_mfma_scale_f32_16x16x128_f8f6f4 v[110:113], v[10:17], v[202:209], 0, v1, v182 op_sel_hi:[0,0,0]
	v_mfma_scale_f32_16x16x128_f8f6f4 v[102:105], v[2:9], v[210:217], 0, v1, v182 op_sel_hi:[0,0,0]
	v_mfma_scale_f32_16x16x128_f8f6f4 v[98:101], v[10:17], v[210:217], 0, v1, v182 op_sel_hi:[0,0,0]
	s_setprio 0
	s_barrier
	s_add_i32 s83, s63, s45
	s_mov_b32 m0, s83
	ds_read_b128 v[194:197], v191 offset:16384
	ds_read_b128 v[202:205], v191 offset:18432
	ds_read_b128 v[198:201], v192 offset:16384
	ds_read_b128 v[206:209], v192 offset:18432
	ds_read_b128 v[210:213], v191 offset:20480
	ds_read_b128 v[218:221], v191 offset:22528
	ds_read_b128 v[214:217], v192 offset:20480
	ds_read_b128 v[222:225], v192 offset:22528
	global_load_lds_dwordx4 v164, s[34:35]
	s_add_i32 m0, s83, 0x2000
	s_add_u32 s84, s34, 0xb0000
	s_addc_u32 s85, s35, 0
	s_add_i32 s83, s64, s45
	global_load_lds_dwordx4 v168, s[34:35]
	s_mov_b32 m0, s83
	s_nop 0
	global_load_lds_dwordx4 v164, s[84:85]
	s_add_i32 m0, s83, 0x2000
	s_nop 0
	global_load_lds_dwordx4 v168, s[84:85]
	s_mov_b32 m0, s52
	s_nop 0
	global_load_lds_dwordx4 v162, s[40:41]
	s_mov_b32 m0, s53
	s_nop 0
	global_load_lds_dwordx4 v166, s[40:41]
	s_waitcnt vmcnt(8)
	s_waitcnt lgkmcnt(0)
	s_barrier
	s_setprio 1
	s_waitcnt lgkmcnt(0)
	v_mfma_scale_f32_16x16x128_f8f6f4 v[94:97], v[18:25], v[194:201], 0, v1, v182 op_sel_hi:[0,0,0]
	v_mfma_scale_f32_16x16x128_f8f6f4 v[90:93], v[26:33], v[194:201], 0, v1, v182 op_sel_hi:[0,0,0]
	v_mfma_scale_f32_16x16x128_f8f6f4 v[82:85], v[18:25], v[202:209], 0, v1, v182 op_sel_hi:[0,0,0]
	v_mfma_scale_f32_16x16x128_f8f6f4 v[74:77], v[26:33], v[202:209], 0, v1, v182 op_sel_hi:[0,0,0]
	v_mfma_scale_f32_16x16x128_f8f6f4 v[66:69], v[18:25], v[210:217], 0, v1, v182 op_sel_hi:[0,0,0]
	v_mfma_scale_f32_16x16x128_f8f6f4 v[58:61], v[26:33], v[210:217], 0, v1, v182 op_sel_hi:[0,0,0]
	v_mfma_scale_f32_16x16x128_f8f6f4 v[50:53], v[18:25], v[218:225], 0, v1, v182 op_sel_hi:[0,0,0]
	v_mfma_scale_f32_16x16x128_f8f6f4 v[42:45], v[26:33], v[218:225], 0, v1, v182 op_sel_hi:[0,0,0]
	s_setprio 0
	s_setprio 1
	v_mfma_scale_f32_16x16x128_f8f6f4 v[86:89], v[2:9], v[194:201], 0, v1, v182 op_sel_hi:[0,0,0]
	v_mfma_scale_f32_16x16x128_f8f6f4 v[78:81], v[10:17], v[194:201], 0, v1, v182 op_sel_hi:[0,0,0]
	v_mfma_scale_f32_16x16x128_f8f6f4 v[70:73], v[2:9], v[202:209], 0, v1, v182 op_sel_hi:[0,0,0]
	v_mfma_scale_f32_16x16x128_f8f6f4 v[62:65], v[10:17], v[202:209], 0, v1, v182 op_sel_hi:[0,0,0]
	v_mfma_scale_f32_16x16x128_f8f6f4 v[54:57], v[2:9], v[210:217], 0, v1, v182 op_sel_hi:[0,0,0]
	v_mfma_scale_f32_16x16x128_f8f6f4 v[46:49], v[10:17], v[210:217], 0, v1, v182 op_sel_hi:[0,0,0]
	v_mfma_scale_f32_16x16x128_f8f6f4 v[38:41], v[2:9], v[218:225], 0, v1, v182 op_sel_hi:[0,0,0]
	v_mfma_scale_f32_16x16x128_f8f6f4 v[34:37], v[10:17], v[218:225], 0, v1, v182 op_sel_hi:[0,0,0]
	s_setprio 0
	s_barrier
	s_branch .Lmid_5

; #define PG8_STAGE(bufoff, gbase, voff) do { _Pragma("unroll") for (int _i = 0; _i < 2; ++_i) \
;         __builtin_amdgcn_global_load_lds((const unsigned*)((const char*)(gbase) + (voff)[_i]), (PG8_LAS unsigned*)(lds + (bufoff) + ldsw + _i * 8192), 16, 0, 0); } while (0)
; #define PG8_LDA(dst, b, h) do { _Pragma("unroll") for (int m = 0; m < 4; ++m) _Pragma("unroll") for (int k = 0; k < 2; ++k) dst[m][k] = *(const PG8_LAS bf16x8*)(lds + PG8_SA(b, h) + aoff + m * 2048 + k * 1024); } while (0)
; #define PG8_LDB(dst, b, h) do { _Pragma("unroll") for (int n = 0; n < 2; ++n) _Pragma("unroll") for (int k = 0; k < 2; ++k) dst[n][k] = *(const PG8_LAS bf16x8*)(lds + PG8_SB(b, h) + boff + n * 2048 + k * 1024); } while (0)
; #define PG8_BAR __builtin_amdgcn_s_barrier()
; template <class Epi, class Sched, bool ALIGN_EPI = false>
; __device__ __forceinline__ void gemm_phase8(PG8_LAS unsigned char* lds, const Gemm g, const Sched& S, const Epi& E) {
;     ...
;         for (int t = 0; t < nt; t += 2) {
;             const bool last = (t == nt - 2);
;             const char* a1 = cA + (size_t)(t + 1) * kstep;
;             const char* a2 = last ? nA : cA + (size_t)(t + 2) * kstep; const char* b2 = last ? nB : cB + (size_t)(t + 2) * kstep;
;             const char* a3 = a2 + kstep; const char* b3 = b2 + kstep;
;             if (last && has_next) S.a_ready(nxt);
;             PG8_LDB(B0, 0, 0); PG8_LDB(B1, 0, 1); PG8_SCHED; PG8_LDA(At, 0, 0); PG8_STAGE(PG8_SA(1, 1), a1 + hstepA, voffA);
;             PG8_WAIT_V(8); PG8_WAIT_L(0); PG8_BAR; PG8_MMA(0, 0, At, B0); PG8_MMA(0, 1, At, B1); PG8_BAR; PG8_SCHED;
;             PG8_LDA(At, 0, 1); PG8_STAGE(PG8_SB(0, 0), b2, voffB); PG8_STAGE(PG8_SB(0, 1), b2 + hstepB, voffB); PG8_STAGE(PG8_SA(0, 0), a2, voffA);
;             PG8_WAIT_V(8); PG8_WAIT_L(0); PG8_BAR; PG8_MMA(1, 0, At, B0); PG8_MMA(1, 1, At, B1); PG8_BAR; PG8_SCHED;
;             PG8_LDB(B0, 1, 0); PG8_LDB(B1, 1, 1); PG8_SCHED; PG8_LDA(At, 1, 0); PG8_STAGE(PG8_SA(0, 1), a2 + hstepA, voffA);
;             PG8_WAIT_V(8); PG8_WAIT_L(0); PG8_BAR; PG8_MMA(0, 0, At, B0); PG8_MMA(0, 1, At, B1); PG8_BAR; PG8_SCHED;
;             PG8_LDA(At, 1, 1); PG8_STAGE(PG8_SB(1, 0), b3, voffB); PG8_STAGE(PG8_SB(1, 1), b3 + hstepB, voffB); PG8_STAGE(PG8_SA(1, 0), a3, voffA);
;             PG8_WAIT_V(8); PG8_WAIT_L(0); PG8_BAR; PG8_MMA(1, 0, At, B0); PG8_MMA(1, 1, At, B1); PG8_BAR; PG8_SCHED;
;         }
.Lmid_5:
	s_add_i32 s83, 0, 0x18000
	s_add_i32 s84, 0, 0x1c000
	v_add_u32_e32 v6, s83, v184
	v_add_u32_e32 v14, s83, v185
	v_add_u32_e32 v22, s84, v184
	v_add_u32_e32 v30, s84, v185
	ds_read_b128 v[2:5], v6
	ds_read_b128 v[10:13], v6 offset:2048
	ds_read_b128 v[6:9], v14
	ds_read_b128 v[14:17], v14 offset:2048
	ds_read_b128 v[18:21], v22
	ds_read_b128 v[26:29], v22 offset:2048
	ds_read_b128 v[22:25], v30
	ds_read_b128 v[30:33], v30 offset:2048
	s_add_u32 s40, s40, 0xb0000
	s_addc_u32 s41, s41, 0
	s_mov_b32 m0, s54
	ds_read_b128 v[194:197], v191 offset:32768
	ds_read_b128 v[202:205], v191 offset:34816
	ds_read_b128 v[198:201], v192 offset:32768
	ds_read_b128 v[206:209], v192 offset:34816
	ds_read_b128 v[210:213], v191 offset:36864
	ds_read_b128 v[218:221], v191 offset:38912
	ds_read_b128 v[214:217], v192 offset:36864
	ds_read_b128 v[222:225], v192 offset:38912
	global_load_lds_dwordx4 v162, s[40:41]
	s_mov_b32 m0, s55
	s_nop 0
	global_load_lds_dwordx4 v166, s[40:41]
	s_waitcnt vmcnt(8)
	s_waitcnt lgkmcnt(0)
	s_barrier
	s_setprio 1
	s_waitcnt lgkmcnt(0)
	v_mfma_scale_f32_16x16x128_f8f6f4 v[158:161], v[2:9], v[194:201], v[158:161], v1, v182 op_sel_hi:[0,0,0]
	v_mfma_scale_f32_16x16x128_f8f6f4 v[154:157], v[10:17], v[194:201], v[154:157], v1, v182 op_sel_hi:[0,0,0]
	v_mfma_scale_f32_16x16x128_f8f6f4 v[150:153], v[2:9], v[202:209], v[150:153], v1, v182 op_sel_hi:[0,0,0]
	v_mfma_scale_f32_16x16x128_f8f6f4 v[138:141], v[10:17], v[202:209], v[138:141], v1, v182 op_sel_hi:[0,0,0]
	v_mfma_scale_f32_16x16x128_f8f6f4 v[130:133], v[2:9], v[210:217], v[130:133], v1, v182 op_sel_hi:[0,0,0]
	v_mfma_scale_f32_16x16x128_f8f6f4 v[122:125], v[10:17], v[210:217], v[122:125], v1, v182 op_sel_hi:[0,0,0]
	v_mfma_scale_f32_16x16x128_f8f6f4 v[118:121], v[2:9], v[218:225], v[118:121], v1, v182 op_sel_hi:[0,0,0]
	v_mfma_scale_f32_16x16x128_f8f6f4 v[106:109], v[10:17], v[218:225], v[106:109], v1, v182 op_sel_hi:[0,0,0]
	s_setprio 0
	s_setprio 1
	v_mfma_scale_f32_16x16x128_f8f6f4 v[146:149], v[18:25], v[194:201], v[146:149], v1, v182 op_sel_hi:[0,0,0]
	v_mfma_scale_f32_16x16x128_f8f6f4 v[142:145], v[26:33], v[194:201], v[142:145], v1, v182 op_sel_hi:[0,0,0]
	v_mfma_scale_f32_16x16x128_f8f6f4 v[134:137], v[18:25], v[202:209], v[134:137], v1, v182 op_sel_hi:[0,0,0]
	v_mfma_scale_f32_16x16x128_f8f6f4 v[126:129], v[26:33], v[202:209], v[126:129], v1, v182 op_sel_hi:[0,0,0]
	v_mfma_scale_f32_16x16x128_f8f6f4 v[114:117], v[18:25], v[210:217], v[114:117], v1, v182 op_sel_hi:[0,0,0]
	v_mfma_scale_f32_16x16x128_f8f6f4 v[110:113], v[26:33], v[210:217], v[110:113], v1, v182 op_sel_hi:[0,0,0]
	v_mfma_scale_f32_16x16x128_f8f6f4 v[102:105], v[18:25], v[218:225], v[102:105], v1, v182 op_sel_hi:[0,0,0]
	v_mfma_scale_f32_16x16x128_f8f6f4 v[98:101], v[26:33], v[218:225], v[98:101], v1, v182 op_sel_hi:[0,0,0]
	s_setprio 0
	s_barrier
	s_add_i32 s101, s83, s45
	s_add_u32 s98, s34, s12
	s_addc_u32 s99, s35, s13
	s_mov_b32 m0, s101
	ds_read_b128 v[194:197], v191 offset:49152
	ds_read_b128 v[202:205], v191 offset:51200
	ds_read_b128 v[198:201], v192 offset:49152
	ds_read_b128 v[206:209], v192 offset:51200
	ds_read_b128 v[210:213], v191 offset:53248
	ds_read_b128 v[218:221], v191 offset:55296
	ds_read_b128 v[214:217], v192 offset:53248
	ds_read_b128 v[222:225], v192 offset:55296
	global_load_lds_dwordx4 v164, s[98:99]
	s_add_i32 m0, s101, 0x2000
	s_add_u32 s34, s34, 0xb0080
	s_addc_u32 s35, s35, 0
	s_add_i32 s101, s84, s45
	global_load_lds_dwordx4 v168, s[98:99]
	s_add_u32 s98, s40, s12
	s_addc_u32 s99, s41, s13
	s_sub_u32 s98, s98, 0xb0000
	s_subb_u32 s99, s99, 0
	s_mov_b32 m0, s101
	s_nop 0
	global_load_lds_dwordx4 v164, s[34:35]
	s_add_i32 m0, s101, 0x2000
	s_nop 0
	global_load_lds_dwordx4 v168, s[34:35]
	s_mov_b32 m0, s61
	s_nop 0
	global_load_lds_dwordx4 v162, s[98:99]
	s_mov_b32 m0, s62
	s_nop 0
	global_load_lds_dwordx4 v166, s[98:99]
	s_waitcnt vmcnt(8)
	s_waitcnt lgkmcnt(0)
	s_barrier
	s_setprio 1
	s_waitcnt lgkmcnt(0)
	v_mfma_scale_f32_16x16x128_f8f6f4 v[94:97], v[2:9], v[194:201], v[94:97], v1, v182 op_sel_hi:[0,0,0]
	v_mfma_scale_f32_16x16x128_f8f6f4 v[90:93], v[10:17], v[194:201], v[90:93], v1, v182 op_sel_hi:[0,0,0]
	v_mfma_scale_f32_16x16x128_f8f6f4 v[82:85], v[2:9], v[202:209], v[82:85], v1, v182 op_sel_hi:[0,0,0]
	v_mfma_scale_f32_16x16x128_f8f6f4 v[74:77], v[10:17], v[202:209], v[74:77], v1, v182 op_sel_hi:[0,0,0]
	v_mfma_scale_f32_16x16x128_f8f6f4 v[66:69], v[2:9], v[210:217], v[66:69], v1, v182 op_sel_hi:[0,0,0]
	v_mfma_scale_f32_16x16x128_f8f6f4 v[58:61], v[10:17], v[210:217], v[58:61], v1, v182 op_sel_hi:[0,0,0]
	v_mfma_scale_f32_16x16x128_f8f6f4 v[50:53], v[2:9], v[218:225], v[50:53], v1, v182 op_sel_hi:[0,0,0]
	v_mfma_scale_f32_16x16x128_f8f6f4 v[42:45], v[10:17], v[218:225], v[42:45], v1, v182 op_sel_hi:[0,0,0]
	s_setprio 0
	s_setprio 1
	v_mfma_scale_f32_16x16x128_f8f6f4 v[86:89], v[18:25], v[194:201], v[86:89], v1, v182 op_sel_hi:[0,0,0]
	v_mfma_scale_f32_16x16x128_f8f6f4 v[78:81], v[26:33], v[194:201], v[78:81], v1, v182 op_sel_hi:[0,0,0]
	v_mfma_scale_f32_16x16x128_f8f6f4 v[70:73], v[18:25], v[202:209], v[70:73], v1, v182 op_sel_hi:[0,0,0]
	v_mfma_scale_f32_16x16x128_f8f6f4 v[62:65], v[26:33], v[202:209], v[62:65], v1, v182 op_sel_hi:[0,0,0]
	v_mfma_scale_f32_16x16x128_f8f6f4 v[54:57], v[18:25], v[210:217], v[54:57], v1, v182 op_sel_hi:[0,0,0]
	v_mfma_scale_f32_16x16x128_f8f6f4 v[46:49], v[26:33], v[210:217], v[46:49], v1, v182 op_sel_hi:[0,0,0]
	v_mfma_scale_f32_16x16x128_f8f6f4 v[38:41], v[18:25], v[218:225], v[38:41], v1, v182 op_sel_hi:[0,0,0]
	v_mfma_scale_f32_16x16x128_f8f6f4 v[34:37], v[26:33], v[218:225], v[34:37], v1, v182 op_sel_hi:[0,0,0]
	s_setprio 0
	s_barrier
	s_add_u32 s38, s38, 0x100
	s_addc_u32 s39, s39, 0
	s_add_u32 s80, s80, 0x100
	s_addc_u32 s81, s81, 0
	s_cmp_ge_u32 s82, s31
	s_mov_b32 s40, s82
	s_cbranch_scc0 .LBB0_1511
	s_and_b64 vcc, exec, s[14:15]
	s_cbranch_vccz .LBB0_1514
	s_barrier
